# hand-written wave-independent S5 chunk-local scan (static tasks, no queue/barriers) replaces s5_local queue items
# speedup vs baseline: 1.2212x; 1.0158x over previous
.LBB0_34:
	s_andn2_b64 vcc, exec, s[36:37]
	v_writelane_b32 v235, s61, 55
	s_cbranch_vccnz .LBB0_764
	s_add_i32 s30, s64, -1
	s_mul_hi_i32 s31, s30, 0x66666667
	s_lshr_b32 s35, s31, 31
	s_ashr_i32 s31, s31, 2
	s_add_i32 s36, s31, s35
	s_mul_i32 s31, s36, 10
	s_sub_i32 s5, s30, s31
	s_lshl_b32 s30, s64, 5
	s_ashr_i32 s31, s30, 31
	s_lshl_b64 s[30:31], s[30:31], 2
	v_readlane_b32 s4, v237, 59
	s_add_u32 s6, s4, s30
	v_readlane_b32 s4, v237, 60
	s_addc_u32 s7, s4, s31
	s_add_i32 s30, s64, 8
	v_writelane_b32 v235, s6, 56
	s_cmp_lt_u32 s30, 19
	s_cselect_b32 s17, s69, s95
	v_writelane_b32 v235, s7, 57
	s_cselect_b32 s16, s68, s94
	s_cselect_b32 s31, s71, s67
	s_cselect_b32 s30, s70, s66
	s_lshl_b32 s6, s36, 10
	s_ashr_i32 s7, s6, 31
	v_writelane_b32 v235, s6, 58
	s_mul_i32 s4, s36, 3
	s_ashr_i32 s37, s36, 31
	v_writelane_b32 v235, s7, 59
	s_lshl_b32 s6, s36, 8
	v_writelane_b32 v235, s4, 60
	s_ashr_i32 s7, s6, 31
	v_writelane_b32 v235, s6, 61
	s_cmp_eq_u32 s5, 8
	s_cbranch_scc1 .Lgm_f1_entry
	s_cmp_eq_u32 s5, 9
	s_cbranch_scc1 .Lgm_f2_entry
	s_cmp_eq_u32 s5, 6
	s_cbranch_scc1 .Lgm_wo_entry
	s_cmp_eq_u32 s5, 1
	s_cbranch_scc1 .Lgm_wi_entry
	s_cmp_eq_u32 s5, 2
	s_cbranch_scc1 .Ls5l_entry
.Ls5l_back:
	s_cmp_lt_i32 s5, 4
	s_mov_b64 s[38:39], -1
	v_writelane_b32 v235, s7, 62
	v_writelane_b32 v235, s5, 63
	s_cbranch_scc1 .LBB0_561
	s_mul_i32 s38, s36, 0x12000
	v_readlane_b32 s4, v236, 3
	s_mul_hi_i32 s35, s36, 0x12000
	v_readlane_b32 s5, v236, 4
	s_add_u32 s54, s4, s38
	s_addc_u32 s55, s5, s35
	s_add_i32 s56, s61, 0xff
	v_readlane_b32 s4, v235, 63
	s_cmp_lt_i32 s4, 7
	s_mov_b64 s[38:39], -1
	s_cbranch_scc1 .LBB0_192
	v_readlane_b32 s4, v235, 63
	s_cmp_lt_i32 s4, 8
	s_cbranch_scc1 .LBB0_182
	s_lshl_b64 s[44:45], s[36:37], 23
	v_readlane_b32 s4, v235, 63
	s_cmp_lt_i32 s4, 9
	s_cbranch_scc1 .LBB0_158
	v_readlane_b32 s4, v235, 63
	s_cmp_eq_u32 s4, 9
	s_cbranch_scc0 .LBB0_157
	s_branch .LBB0_157

.Ls5l_entry:
	v_and_b32_e32 v3, 63, v206
	v_lshrrev_b32_e32 v194, 6, v206
	v_and_b32_e32 v4, 15, v3
	v_readfirstlane_b32 s40, v194
	v_lshrrev_b32_e32 v5, 4, v3
	s_lshl_b32 s41, s63, 3
	s_add_u32 s41, s41, s40
	s_mul_i32 s42, s40, 16896
	v_mul_u32_u24_e32 v6, 2112, v5
	v_lshl_add_u32 v6, v4, 2, v6
	v_add_u32_e32 v6, s42, v6
	v_lshl_add_u32 v7, v3, 3, 0
	v_add_u32_e32 v7, s42, v7
	v_and_b32_e32 v8, 1, v5
	v_lshlrev_b32_e32 v8, 4, v8
	v_lshl_add_u32 v8, v4, 5, v8
	v_lshlrev_b32_e32 v9, 5, v3
	v_lshlrev_b32_e32 v10, 3, v3
	s_add_u32 s43, s41, 0
	s_lshr_b32 s98, s43, 5
	s_bfe_u32 s99, s43, 0x40001
	s_and_b32 s54, s43, 1
	s_cmpk_lt_u32 s98, 0x80
	s_cbranch_scc1 .Ls5l_ctx0
	s_sub_u32 s100, s98, 0x80
	s_lshr_b32 s101, s100, 5
	s_and_b32 s100, s100, 31
	s_lshl_b32 s101, s101, 10
	s_lshl_b32 s100, s100, 1
	s_add_u32 s100, s100, s101
	s_add_u32 s100, s100, 0x1000
	s_mov_b32 s52, 0x91000
	s_movk_i32 s53, 0x2440
	s_branch .Ls5l_rows0
.Ls5l_ctx0:
	s_lshl_b32 s100, s98, 5
	s_movk_i32 s52, 0x2440
	s_mov_b32 s53, 0x24400
.Ls5l_rows0:
	s_mul_i32 s100, s100, 0x2440
	s_lshl_b32 s101, s99, 6
	s_add_u32 s100, s100, s101
	s_add_u32 s100, s100, 0x3a26040
	s_add_u32 s44, s96, s100
	s_addc_u32 s45, s97, 0
	s_lshl_b32 s101, s36, 1
	s_add_u32 s101, s101, s54
	s_lshl_b32 s101, s101, 4
	s_add_u32 s101, s101, s99
	s_lshl_b32 s100, s101, 12
	s_add_u32 s100, s100, 0xd1c4000
	s_add_u32 s46, s96, s100
	s_addc_u32 s47, s97, 0
	s_lshl_b32 s100, s101, 11
	s_add_u32 s100, s100, 0xd1a4000
	s_add_u32 s48, s96, s100
	s_addc_u32 s49, s97, 0
	s_lshl_b32 s100, s98, 4
	s_add_u32 s100, s100, s99
	s_lshl_b32 s100, s100, 1
	s_add_u32 s100, s100, s54
	s_lshl_b32 s100, s100, 9
	s_add_u32 s100, s100, 0xcba4000
	s_add_u32 s50, s96, s100
	s_addc_u32 s51, s97, 0
	v_mul_lo_u32 v11, v4, s52
	v_lshl_add_u32 v11, v5, 5, v11
	v_add_u32_e32 v12, s53, v11
	v_mov_b32_e32 v20, 0
	v_mov_b32_e32 v21, 0
	v_mov_b32_e32 v22, 0
	v_mov_b32_e32 v23, 0
	v_mov_b32_e32 v24, 0
	v_mov_b32_e32 v25, 0
	v_mov_b32_e32 v26, 0
	v_mov_b32_e32 v27, 0
	v_mov_b32_e32 v28, 0
	v_mov_b32_e32 v29, 0
	v_mov_b32_e32 v30, 0
	v_mov_b32_e32 v31, 0
	v_mov_b32_e32 v32, 0
	v_mov_b32_e32 v33, 0
	v_mov_b32_e32 v34, 0
	v_mov_b32_e32 v35, 0
	s_mov_b64 s[38:39], exec
	s_mov_b32 exec_lo, -1
	s_mov_b32 exec_hi, 0
	global_load_dwordx4 v[20:23], v11, s[44:45]
	global_load_dwordx4 v[24:27], v11, s[44:45] offset:16
	global_load_dwordx4 v[28:31], v12, s[44:45]
	global_load_dwordx4 v[32:35], v12, s[44:45] offset:16
	s_mov_b64 exec, s[38:39]
	global_load_dwordx4 v[36:39], v8, s[46:47]
	global_load_dwordx4 v[40:43], v8, s[46:47] offset:512
	global_load_dwordx4 v[44:47], v8, s[46:47] offset:1024
	global_load_dwordx4 v[48:51], v8, s[46:47] offset:1536
	global_load_dwordx4 v[52:55], v8, s[46:47] offset:2048
	global_load_dwordx4 v[56:59], v8, s[46:47] offset:2560
	global_load_dwordx4 v[60:63], v8, s[46:47] offset:3072
	global_load_dwordx4 v[64:67], v8, s[46:47] offset:3584
	global_load_dwordx2 v[68:69], v9, s[48:49]
	s_add_u32 s43, s41, 2048
	s_lshr_b32 s98, s43, 5
	s_bfe_u32 s99, s43, 0x40001
	s_and_b32 s55, s43, 1
	s_cmpk_lt_u32 s98, 0x80
	s_cbranch_scc1 .Ls5l_ctx1
	s_sub_u32 s100, s98, 0x80
	s_lshr_b32 s101, s100, 5
	s_and_b32 s100, s100, 31
	s_lshl_b32 s101, s101, 10
	s_lshl_b32 s100, s100, 1
	s_add_u32 s100, s100, s101
	s_add_u32 s100, s100, 0x1000
	s_mov_b32 s52, 0x91000
	s_movk_i32 s53, 0x2440
	s_branch .Ls5l_rows1

.Ls5l_rows1:
	s_mul_i32 s100, s100, 0x2440
	s_lshl_b32 s101, s99, 6
	s_add_u32 s100, s100, s101
	s_add_u32 s100, s100, 0x3a26040
	s_add_u32 s44, s96, s100
	s_addc_u32 s45, s97, 0
	s_lshl_b32 s101, s36, 1
	s_add_u32 s101, s101, s55
	s_lshl_b32 s101, s101, 4
	s_add_u32 s101, s101, s99
	s_lshl_b32 s100, s101, 12
	s_add_u32 s100, s100, 0xd1c4000
	s_add_u32 s46, s96, s100
	s_addc_u32 s47, s97, 0
	s_lshl_b32 s100, s101, 11
	s_add_u32 s100, s100, 0xd1a4000
	s_add_u32 s48, s96, s100
	s_addc_u32 s49, s97, 0
	s_lshl_b32 s100, s98, 4
	s_add_u32 s100, s100, s99
	s_lshl_b32 s100, s100, 1
	s_add_u32 s100, s100, s55
	s_lshl_b32 s100, s100, 9
	s_add_u32 s100, s100, 0xcba4000
	s_add_u32 s56, s96, s100
	s_addc_u32 s57, s97, 0
	v_mul_lo_u32 v11, v4, s52
	v_lshl_add_u32 v11, v5, 5, v11
	v_add_u32_e32 v12, s53, v11
	v_mov_b32_e32 v70, 0
	v_mov_b32_e32 v71, 0
	v_mov_b32_e32 v72, 0
	v_mov_b32_e32 v73, 0
	v_mov_b32_e32 v74, 0
	v_mov_b32_e32 v75, 0
	v_mov_b32_e32 v76, 0
	v_mov_b32_e32 v77, 0
	v_mov_b32_e32 v78, 0
	v_mov_b32_e32 v79, 0
	v_mov_b32_e32 v80, 0
	v_mov_b32_e32 v81, 0
	v_mov_b32_e32 v82, 0
	v_mov_b32_e32 v83, 0
	v_mov_b32_e32 v84, 0
	v_mov_b32_e32 v85, 0
	s_mov_b64 s[38:39], exec
	s_mov_b32 exec_lo, -1
	s_mov_b32 exec_hi, 0
	global_load_dwordx4 v[70:73], v11, s[44:45]
	global_load_dwordx4 v[74:77], v11, s[44:45] offset:16
	global_load_dwordx4 v[78:81], v12, s[44:45]
	global_load_dwordx4 v[82:85], v12, s[44:45] offset:16
	s_mov_b64 exec, s[38:39]
	global_load_dwordx4 v[86:89], v8, s[46:47]
	global_load_dwordx4 v[90:93], v8, s[46:47] offset:512
	global_load_dwordx4 v[94:97], v8, s[46:47] offset:1024
	global_load_dwordx4 v[98:101], v8, s[46:47] offset:1536
	global_load_dwordx4 v[102:105], v8, s[46:47] offset:2048
	global_load_dwordx4 v[106:109], v8, s[46:47] offset:2560
	global_load_dwordx4 v[110:113], v8, s[46:47] offset:3072
	global_load_dwordx4 v[114:117], v8, s[46:47] offset:3584
	global_load_dwordx2 v[118:119], v9, s[48:49]
	s_waitcnt vmcnt(13)
	v_cvt_pk_bf16_f32 v120, v20, v21
	v_cvt_pk_bf16_f32 v121, v22, v23
	v_cvt_pk_bf16_f32 v122, v24, v25
	v_cvt_pk_bf16_f32 v123, v26, v27
	v_cvt_pk_bf16_f32 v124, v28, v29
	v_cvt_pk_bf16_f32 v125, v30, v31
	v_cvt_pk_bf16_f32 v126, v32, v33
	v_cvt_pk_bf16_f32 v127, v34, v35
	s_nop 1
	v_mfma_f32_16x16x32_bf16 v[128:131], v[120:123], v[36:39], 0
	v_mfma_f32_16x16x32_bf16 v[132:135], v[124:127], v[36:39], 0
	v_mfma_f32_16x16x32_bf16 v[136:139], v[120:123], v[40:43], 0
	v_mfma_f32_16x16x32_bf16 v[140:143], v[124:127], v[40:43], 0
	v_mfma_f32_16x16x32_bf16 v[144:147], v[120:123], v[44:47], 0
	v_mfma_f32_16x16x32_bf16 v[148:151], v[124:127], v[44:47], 0
	v_mfma_f32_16x16x32_bf16 v[152:155], v[120:123], v[48:51], 0
	v_mfma_f32_16x16x32_bf16 v[156:159], v[124:127], v[48:51], 0
	v_mfma_f32_16x16x32_bf16 v[160:163], v[120:123], v[52:55], 0
	v_mfma_f32_16x16x32_bf16 v[164:167], v[124:127], v[52:55], 0
	v_mfma_f32_16x16x32_bf16 v[168:171], v[120:123], v[56:59], 0
	v_mfma_f32_16x16x32_bf16 v[172:175], v[124:127], v[56:59], 0
	v_mfma_f32_16x16x32_bf16 v[176:179], v[120:123], v[60:63], 0
	v_mfma_f32_16x16x32_bf16 v[180:183], v[124:127], v[60:63], 0
	v_mfma_f32_16x16x32_bf16 v[184:187], v[120:123], v[64:67], 0
	v_mfma_f32_16x16x32_bf16 v[188:191], v[124:127], v[64:67], 0
	ds_write_b32 v6, v128 offset:0
	ds_write_b32 v6, v129 offset:528
	ds_write_b32 v6, v130 offset:1056
	ds_write_b32 v6, v131 offset:1584
	ds_write_b32 v6, v132 offset:8448
	ds_write_b32 v6, v133 offset:8976
	ds_write_b32 v6, v134 offset:9504
	ds_write_b32 v6, v135 offset:10032
	ds_write_b32 v6, v136 offset:64
	ds_write_b32 v6, v137 offset:592
	ds_write_b32 v6, v138 offset:1120
	ds_write_b32 v6, v139 offset:1648
	ds_write_b32 v6, v140 offset:8512
	ds_write_b32 v6, v141 offset:9040
	ds_write_b32 v6, v142 offset:9568
	ds_write_b32 v6, v143 offset:10096
	ds_write_b32 v6, v144 offset:128
	ds_write_b32 v6, v145 offset:656
	ds_write_b32 v6, v146 offset:1184
	ds_write_b32 v6, v147 offset:1712
	ds_write_b32 v6, v148 offset:8576
	ds_write_b32 v6, v149 offset:9104
	ds_write_b32 v6, v150 offset:9632
	ds_write_b32 v6, v151 offset:10160
	ds_write_b32 v6, v152 offset:192
	ds_write_b32 v6, v153 offset:720
	ds_write_b32 v6, v154 offset:1248
	ds_write_b32 v6, v155 offset:1776
	ds_write_b32 v6, v156 offset:8640
	ds_write_b32 v6, v157 offset:9168
	ds_write_b32 v6, v158 offset:9696
	ds_write_b32 v6, v159 offset:10224
	ds_write_b32 v6, v160 offset:256
	ds_write_b32 v6, v161 offset:784
	ds_write_b32 v6, v162 offset:1312
	ds_write_b32 v6, v163 offset:1840
	ds_write_b32 v6, v164 offset:8704
	ds_write_b32 v6, v165 offset:9232
	ds_write_b32 v6, v166 offset:9760
	ds_write_b32 v6, v167 offset:10288
	ds_write_b32 v6, v168 offset:320
	ds_write_b32 v6, v169 offset:848
	ds_write_b32 v6, v170 offset:1376
	ds_write_b32 v6, v171 offset:1904
	ds_write_b32 v6, v172 offset:8768
	ds_write_b32 v6, v173 offset:9296
	ds_write_b32 v6, v174 offset:9824
	ds_write_b32 v6, v175 offset:10352
	ds_write_b32 v6, v176 offset:384
	ds_write_b32 v6, v177 offset:912
	ds_write_b32 v6, v178 offset:1440
	ds_write_b32 v6, v179 offset:1968
	ds_write_b32 v6, v180 offset:8832
	ds_write_b32 v6, v181 offset:9360
	ds_write_b32 v6, v182 offset:9888
	ds_write_b32 v6, v183 offset:10416
	ds_write_b32 v6, v184 offset:448
	ds_write_b32 v6, v185 offset:976
	ds_write_b32 v6, v186 offset:1504
	ds_write_b32 v6, v187 offset:2032
	s_nop 4
	ds_write_b32 v6, v188 offset:8896
	ds_write_b32 v6, v189 offset:9424
	ds_write_b32 v6, v190 offset:9952
	ds_write_b32 v6, v191 offset:10480
	v_mov_b32_e32 v192, 0
	v_mov_b32_e32 v193, 0
	s_waitcnt lgkmcnt(0)
	s_cmp_eq_u32 s54, 0
	s_cbranch_scc0 .Ls5l_bwd0
	ds_read_b64 v[128:129], v7 offset:0
	ds_read_b64 v[130:131], v7 offset:528
	ds_read_b64 v[132:133], v7 offset:1056
	ds_read_b64 v[134:135], v7 offset:1584
	ds_read_b64 v[136:137], v7 offset:2112
	ds_read_b64 v[138:139], v7 offset:2640
	ds_read_b64 v[140:141], v7 offset:3168
	ds_read_b64 v[142:143], v7 offset:3696
	ds_read_b64 v[144:145], v7 offset:4224
	ds_read_b64 v[146:147], v7 offset:4752
	ds_read_b64 v[148:149], v7 offset:5280
	ds_read_b64 v[150:151], v7 offset:5808
	ds_read_b64 v[152:153], v7 offset:6336
	ds_read_b64 v[154:155], v7 offset:6864
	ds_read_b64 v[156:157], v7 offset:7392
	ds_read_b64 v[158:159], v7 offset:7920
	s_waitcnt lgkmcnt(15)
	v_mul_f32_e32 v194, v69, v193
	v_mul_f32_e32 v195, v69, v192
	v_fma_f32 v0, v68, v192, -v194
	v_fma_f32 v1, v68, v193, v195
	v_add_f32_e32 v192, v0, v128
	v_add_f32_e32 v193, v1, v129
	s_waitcnt lgkmcnt(14)
	v_mul_f32_e32 v194, v69, v193
	v_mul_f32_e32 v195, v69, v192
	v_fma_f32 v0, v68, v192, -v194
	v_fma_f32 v1, v68, v193, v195
	v_add_f32_e32 v192, v0, v130
	v_add_f32_e32 v193, v1, v131
	s_waitcnt lgkmcnt(13)
	v_mul_f32_e32 v194, v69, v193
	v_mul_f32_e32 v195, v69, v192
	v_fma_f32 v0, v68, v192, -v194
	v_fma_f32 v1, v68, v193, v195
	v_add_f32_e32 v192, v0, v132
	v_add_f32_e32 v193, v1, v133
	s_waitcnt lgkmcnt(12)
	v_mul_f32_e32 v194, v69, v193
	v_mul_f32_e32 v195, v69, v192
	v_fma_f32 v0, v68, v192, -v194
	v_fma_f32 v1, v68, v193, v195
	v_add_f32_e32 v192, v0, v134
	v_add_f32_e32 v193, v1, v135
	s_waitcnt lgkmcnt(11)
	v_mul_f32_e32 v194, v69, v193
	v_mul_f32_e32 v195, v69, v192
	v_fma_f32 v0, v68, v192, -v194
	v_fma_f32 v1, v68, v193, v195
	v_add_f32_e32 v192, v0, v136
	v_add_f32_e32 v193, v1, v137
	s_waitcnt lgkmcnt(10)
	v_mul_f32_e32 v194, v69, v193
	v_mul_f32_e32 v195, v69, v192
	v_fma_f32 v0, v68, v192, -v194
	v_fma_f32 v1, v68, v193, v195
	v_add_f32_e32 v192, v0, v138
	v_add_f32_e32 v193, v1, v139
	s_waitcnt lgkmcnt(9)
	v_mul_f32_e32 v194, v69, v193
	v_mul_f32_e32 v195, v69, v192
	v_fma_f32 v0, v68, v192, -v194
	v_fma_f32 v1, v68, v193, v195
	v_add_f32_e32 v192, v0, v140
	v_add_f32_e32 v193, v1, v141
	s_waitcnt lgkmcnt(8)
	v_mul_f32_e32 v194, v69, v193
	v_mul_f32_e32 v195, v69, v192
	v_fma_f32 v0, v68, v192, -v194
	v_fma_f32 v1, v68, v193, v195
	v_add_f32_e32 v192, v0, v142
	v_add_f32_e32 v193, v1, v143
	ds_read_b64 v[128:129], v7 offset:8448
	ds_read_b64 v[130:131], v7 offset:8976
	ds_read_b64 v[132:133], v7 offset:9504
	ds_read_b64 v[134:135], v7 offset:10032
	ds_read_b64 v[136:137], v7 offset:10560
	ds_read_b64 v[138:139], v7 offset:11088
	ds_read_b64 v[140:141], v7 offset:11616
	ds_read_b64 v[142:143], v7 offset:12144
	s_waitcnt lgkmcnt(15)
	v_mul_f32_e32 v194, v69, v193
	v_mul_f32_e32 v195, v69, v192
	v_fma_f32 v0, v68, v192, -v194
	v_fma_f32 v1, v68, v193, v195
	v_add_f32_e32 v192, v0, v144
	v_add_f32_e32 v193, v1, v145
	s_waitcnt lgkmcnt(14)
	v_mul_f32_e32 v194, v69, v193
	v_mul_f32_e32 v195, v69, v192
	v_fma_f32 v0, v68, v192, -v194
	v_fma_f32 v1, v68, v193, v195
	v_add_f32_e32 v192, v0, v146
	v_add_f32_e32 v193, v1, v147
	s_waitcnt lgkmcnt(13)
	v_mul_f32_e32 v194, v69, v193
	v_mul_f32_e32 v195, v69, v192
	v_fma_f32 v0, v68, v192, -v194
	v_fma_f32 v1, v68, v193, v195
	v_add_f32_e32 v192, v0, v148
	v_add_f32_e32 v193, v1, v149
	s_waitcnt lgkmcnt(12)
	v_mul_f32_e32 v194, v69, v193
	v_mul_f32_e32 v195, v69, v192
	v_fma_f32 v0, v68, v192, -v194
	v_fma_f32 v1, v68, v193, v195
	v_add_f32_e32 v192, v0, v150
	v_add_f32_e32 v193, v1, v151
	s_waitcnt lgkmcnt(11)
	v_mul_f32_e32 v194, v69, v193
	v_mul_f32_e32 v195, v69, v192
	v_fma_f32 v0, v68, v192, -v194
	v_fma_f32 v1, v68, v193, v195
	v_add_f32_e32 v192, v0, v152
	v_add_f32_e32 v193, v1, v153
	s_waitcnt lgkmcnt(10)
	v_mul_f32_e32 v194, v69, v193
	v_mul_f32_e32 v195, v69, v192
	v_fma_f32 v0, v68, v192, -v194
	v_fma_f32 v1, v68, v193, v195
	v_add_f32_e32 v192, v0, v154
	v_add_f32_e32 v193, v1, v155
	s_waitcnt lgkmcnt(9)
	v_mul_f32_e32 v194, v69, v193
	v_mul_f32_e32 v195, v69, v192
	v_fma_f32 v0, v68, v192, -v194
	v_fma_f32 v1, v68, v193, v195
	v_add_f32_e32 v192, v0, v156
	v_add_f32_e32 v193, v1, v157
	s_waitcnt lgkmcnt(8)
	v_mul_f32_e32 v194, v69, v193
	v_mul_f32_e32 v195, v69, v192
	v_fma_f32 v0, v68, v192, -v194
	v_fma_f32 v1, v68, v193, v195
	v_add_f32_e32 v192, v0, v158
	v_add_f32_e32 v193, v1, v159
	ds_read_b64 v[144:145], v7 offset:12672
	ds_read_b64 v[146:147], v7 offset:13200
	ds_read_b64 v[148:149], v7 offset:13728
	ds_read_b64 v[150:151], v7 offset:14256
	ds_read_b64 v[152:153], v7 offset:14784
	ds_read_b64 v[154:155], v7 offset:15312
	ds_read_b64 v[156:157], v7 offset:15840
	ds_read_b64 v[158:159], v7 offset:16368
	s_waitcnt lgkmcnt(15)
	v_mul_f32_e32 v194, v69, v193
	v_mul_f32_e32 v195, v69, v192
	v_fma_f32 v0, v68, v192, -v194
	v_fma_f32 v1, v68, v193, v195
	v_add_f32_e32 v192, v0, v128
	v_add_f32_e32 v193, v1, v129
	s_waitcnt lgkmcnt(14)
	v_mul_f32_e32 v194, v69, v193
	v_mul_f32_e32 v195, v69, v192
	v_fma_f32 v0, v68, v192, -v194
	v_fma_f32 v1, v68, v193, v195
	v_add_f32_e32 v192, v0, v130
	v_add_f32_e32 v193, v1, v131
	s_waitcnt lgkmcnt(13)
	v_mul_f32_e32 v194, v69, v193
	v_mul_f32_e32 v195, v69, v192
	v_fma_f32 v0, v68, v192, -v194
	v_fma_f32 v1, v68, v193, v195
	v_add_f32_e32 v192, v0, v132
	v_add_f32_e32 v193, v1, v133
	s_waitcnt lgkmcnt(12)
	v_mul_f32_e32 v194, v69, v193
	v_mul_f32_e32 v195, v69, v192
	v_fma_f32 v0, v68, v192, -v194
	v_fma_f32 v1, v68, v193, v195
	v_add_f32_e32 v192, v0, v134
	v_add_f32_e32 v193, v1, v135
	s_waitcnt lgkmcnt(11)
	v_mul_f32_e32 v194, v69, v193
	v_mul_f32_e32 v195, v69, v192
	v_fma_f32 v0, v68, v192, -v194
	v_fma_f32 v1, v68, v193, v195
	v_add_f32_e32 v192, v0, v136
	v_add_f32_e32 v193, v1, v137
	s_waitcnt lgkmcnt(10)
	v_mul_f32_e32 v194, v69, v193
	v_mul_f32_e32 v195, v69, v192
	v_fma_f32 v0, v68, v192, -v194
	v_fma_f32 v1, v68, v193, v195
	v_add_f32_e32 v192, v0, v138
	v_add_f32_e32 v193, v1, v139
	s_waitcnt lgkmcnt(9)
	v_mul_f32_e32 v194, v69, v193
	v_mul_f32_e32 v195, v69, v192
	v_fma_f32 v0, v68, v192, -v194
	v_fma_f32 v1, v68, v193, v195
	v_add_f32_e32 v192, v0, v140
	v_add_f32_e32 v193, v1, v141
	s_waitcnt lgkmcnt(8)
	v_mul_f32_e32 v194, v69, v193
	v_mul_f32_e32 v195, v69, v192
	v_fma_f32 v0, v68, v192, -v194
	v_fma_f32 v1, v68, v193, v195
	v_add_f32_e32 v192, v0, v142
	v_add_f32_e32 v193, v1, v143
	s_waitcnt lgkmcnt(7)
	v_mul_f32_e32 v194, v69, v193
	v_mul_f32_e32 v195, v69, v192
	v_fma_f32 v0, v68, v192, -v194
	v_fma_f32 v1, v68, v193, v195
	v_add_f32_e32 v192, v0, v144
	v_add_f32_e32 v193, v1, v145
	s_waitcnt lgkmcnt(6)
	v_mul_f32_e32 v194, v69, v193
	v_mul_f32_e32 v195, v69, v192
	v_fma_f32 v0, v68, v192, -v194
	v_fma_f32 v1, v68, v193, v195
	v_add_f32_e32 v192, v0, v146
	v_add_f32_e32 v193, v1, v147
	s_waitcnt lgkmcnt(5)
	v_mul_f32_e32 v194, v69, v193
	v_mul_f32_e32 v195, v69, v192
	v_fma_f32 v0, v68, v192, -v194
	v_fma_f32 v1, v68, v193, v195
	v_add_f32_e32 v192, v0, v148
	v_add_f32_e32 v193, v1, v149
	s_waitcnt lgkmcnt(4)
	v_mul_f32_e32 v194, v69, v193
	v_mul_f32_e32 v195, v69, v192
	v_fma_f32 v0, v68, v192, -v194
	v_fma_f32 v1, v68, v193, v195
	v_add_f32_e32 v192, v0, v150
	v_add_f32_e32 v193, v1, v151
	s_waitcnt lgkmcnt(3)
	v_mul_f32_e32 v194, v69, v193
	v_mul_f32_e32 v195, v69, v192
	v_fma_f32 v0, v68, v192, -v194
	v_fma_f32 v1, v68, v193, v195
	v_add_f32_e32 v192, v0, v152
	v_add_f32_e32 v193, v1, v153
	s_waitcnt lgkmcnt(2)
	v_mul_f32_e32 v194, v69, v193
	v_mul_f32_e32 v195, v69, v192
	v_fma_f32 v0, v68, v192, -v194
	v_fma_f32 v1, v68, v193, v195
	v_add_f32_e32 v192, v0, v154
	v_add_f32_e32 v193, v1, v155
	s_waitcnt lgkmcnt(1)
	v_mul_f32_e32 v194, v69, v193
	v_mul_f32_e32 v195, v69, v192
	v_fma_f32 v0, v68, v192, -v194
	v_fma_f32 v1, v68, v193, v195
	v_add_f32_e32 v192, v0, v156
	v_add_f32_e32 v193, v1, v157
	s_waitcnt lgkmcnt(0)
	v_mul_f32_e32 v194, v69, v193
	v_mul_f32_e32 v195, v69, v192
	v_fma_f32 v0, v68, v192, -v194
	v_fma_f32 v1, v68, v193, v195
	v_add_f32_e32 v192, v0, v158
	v_add_f32_e32 v193, v1, v159
	s_branch .Ls5l_sdone0
.Ls5l_bwd0:
	ds_read_b64 v[128:129], v7 offset:16368
	ds_read_b64 v[130:131], v7 offset:15840
	ds_read_b64 v[132:133], v7 offset:15312
	ds_read_b64 v[134:135], v7 offset:14784
	ds_read_b64 v[136:137], v7 offset:14256
	ds_read_b64 v[138:139], v7 offset:13728
	ds_read_b64 v[140:141], v7 offset:13200
	ds_read_b64 v[142:143], v7 offset:12672
	ds_read_b64 v[144:145], v7 offset:12144
	ds_read_b64 v[146:147], v7 offset:11616
	ds_read_b64 v[148:149], v7 offset:11088
	ds_read_b64 v[150:151], v7 offset:10560
	ds_read_b64 v[152:153], v7 offset:10032
	ds_read_b64 v[154:155], v7 offset:9504
	ds_read_b64 v[156:157], v7 offset:8976
	ds_read_b64 v[158:159], v7 offset:8448
	s_waitcnt lgkmcnt(15)
	v_mul_f32_e32 v194, v69, v193
	v_mul_f32_e32 v195, v69, v192
	v_fma_f32 v0, v68, v192, -v194
	v_fma_f32 v1, v68, v193, v195
	v_add_f32_e32 v192, v0, v128
	v_add_f32_e32 v193, v1, v129
	s_waitcnt lgkmcnt(14)
	v_mul_f32_e32 v194, v69, v193
	v_mul_f32_e32 v195, v69, v192
	v_fma_f32 v0, v68, v192, -v194
	v_fma_f32 v1, v68, v193, v195
	v_add_f32_e32 v192, v0, v130
	v_add_f32_e32 v193, v1, v131
	s_waitcnt lgkmcnt(13)
	v_mul_f32_e32 v194, v69, v193
	v_mul_f32_e32 v195, v69, v192
	v_fma_f32 v0, v68, v192, -v194
	v_fma_f32 v1, v68, v193, v195
	v_add_f32_e32 v192, v0, v132
	v_add_f32_e32 v193, v1, v133
	s_waitcnt lgkmcnt(12)
	v_mul_f32_e32 v194, v69, v193
	v_mul_f32_e32 v195, v69, v192
	v_fma_f32 v0, v68, v192, -v194
	v_fma_f32 v1, v68, v193, v195
	v_add_f32_e32 v192, v0, v134
	v_add_f32_e32 v193, v1, v135
	s_waitcnt lgkmcnt(11)
	v_mul_f32_e32 v194, v69, v193
	v_mul_f32_e32 v195, v69, v192
	v_fma_f32 v0, v68, v192, -v194
	v_fma_f32 v1, v68, v193, v195
	v_add_f32_e32 v192, v0, v136
	v_add_f32_e32 v193, v1, v137
	s_waitcnt lgkmcnt(10)
	v_mul_f32_e32 v194, v69, v193
	v_mul_f32_e32 v195, v69, v192
	v_fma_f32 v0, v68, v192, -v194
	v_fma_f32 v1, v68, v193, v195
	v_add_f32_e32 v192, v0, v138
	v_add_f32_e32 v193, v1, v139
	s_waitcnt lgkmcnt(9)
	v_mul_f32_e32 v194, v69, v193
	v_mul_f32_e32 v195, v69, v192
	v_fma_f32 v0, v68, v192, -v194
	v_fma_f32 v1, v68, v193, v195
	v_add_f32_e32 v192, v0, v140
	v_add_f32_e32 v193, v1, v141
	s_waitcnt lgkmcnt(8)
	v_mul_f32_e32 v194, v69, v193
	v_mul_f32_e32 v195, v69, v192
	v_fma_f32 v0, v68, v192, -v194
	v_fma_f32 v1, v68, v193, v195
	v_add_f32_e32 v192, v0, v142
	v_add_f32_e32 v193, v1, v143
	ds_read_b64 v[128:129], v7 offset:7920
	ds_read_b64 v[130:131], v7 offset:7392
	ds_read_b64 v[132:133], v7 offset:6864
	ds_read_b64 v[134:135], v7 offset:6336
	ds_read_b64 v[136:137], v7 offset:5808
	ds_read_b64 v[138:139], v7 offset:5280
	ds_read_b64 v[140:141], v7 offset:4752
	ds_read_b64 v[142:143], v7 offset:4224
	s_waitcnt lgkmcnt(15)
	v_mul_f32_e32 v194, v69, v193
	v_mul_f32_e32 v195, v69, v192
	v_fma_f32 v0, v68, v192, -v194
	v_fma_f32 v1, v68, v193, v195
	v_add_f32_e32 v192, v0, v144
	v_add_f32_e32 v193, v1, v145
	s_waitcnt lgkmcnt(14)
	v_mul_f32_e32 v194, v69, v193
	v_mul_f32_e32 v195, v69, v192
	v_fma_f32 v0, v68, v192, -v194
	v_fma_f32 v1, v68, v193, v195
	v_add_f32_e32 v192, v0, v146
	v_add_f32_e32 v193, v1, v147
	s_waitcnt lgkmcnt(13)
	v_mul_f32_e32 v194, v69, v193
	v_mul_f32_e32 v195, v69, v192
	v_fma_f32 v0, v68, v192, -v194
	v_fma_f32 v1, v68, v193, v195
	v_add_f32_e32 v192, v0, v148
	v_add_f32_e32 v193, v1, v149
	s_waitcnt lgkmcnt(12)
	v_mul_f32_e32 v194, v69, v193
	v_mul_f32_e32 v195, v69, v192
	v_fma_f32 v0, v68, v192, -v194
	v_fma_f32 v1, v68, v193, v195
	v_add_f32_e32 v192, v0, v150
	v_add_f32_e32 v193, v1, v151
	s_waitcnt lgkmcnt(11)
	v_mul_f32_e32 v194, v69, v193
	v_mul_f32_e32 v195, v69, v192
	v_fma_f32 v0, v68, v192, -v194
	v_fma_f32 v1, v68, v193, v195
	v_add_f32_e32 v192, v0, v152
	v_add_f32_e32 v193, v1, v153
	s_waitcnt lgkmcnt(10)
	v_mul_f32_e32 v194, v69, v193
	v_mul_f32_e32 v195, v69, v192
	v_fma_f32 v0, v68, v192, -v194
	v_fma_f32 v1, v68, v193, v195
	v_add_f32_e32 v192, v0, v154
	v_add_f32_e32 v193, v1, v155
	s_waitcnt lgkmcnt(9)
	v_mul_f32_e32 v194, v69, v193
	v_mul_f32_e32 v195, v69, v192
	v_fma_f32 v0, v68, v192, -v194
	v_fma_f32 v1, v68, v193, v195
	v_add_f32_e32 v192, v0, v156
	v_add_f32_e32 v193, v1, v157
	s_waitcnt lgkmcnt(8)
	v_mul_f32_e32 v194, v69, v193
	v_mul_f32_e32 v195, v69, v192
	v_fma_f32 v0, v68, v192, -v194
	v_fma_f32 v1, v68, v193, v195
	v_add_f32_e32 v192, v0, v158
	v_add_f32_e32 v193, v1, v159
	ds_read_b64 v[144:145], v7 offset:3696
	ds_read_b64 v[146:147], v7 offset:3168
	ds_read_b64 v[148:149], v7 offset:2640
	ds_read_b64 v[150:151], v7 offset:2112
	ds_read_b64 v[152:153], v7 offset:1584
	ds_read_b64 v[154:155], v7 offset:1056
	ds_read_b64 v[156:157], v7 offset:528
	ds_read_b64 v[158:159], v7 offset:0
	s_waitcnt lgkmcnt(15)
	v_mul_f32_e32 v194, v69, v193
	v_mul_f32_e32 v195, v69, v192
	v_fma_f32 v0, v68, v192, -v194
	v_fma_f32 v1, v68, v193, v195
	v_add_f32_e32 v192, v0, v128
	v_add_f32_e32 v193, v1, v129
	s_waitcnt lgkmcnt(14)
	v_mul_f32_e32 v194, v69, v193
	v_mul_f32_e32 v195, v69, v192
	v_fma_f32 v0, v68, v192, -v194
	v_fma_f32 v1, v68, v193, v195
	v_add_f32_e32 v192, v0, v130
	v_add_f32_e32 v193, v1, v131
	s_waitcnt lgkmcnt(13)
	v_mul_f32_e32 v194, v69, v193
	v_mul_f32_e32 v195, v69, v192
	v_fma_f32 v0, v68, v192, -v194
	v_fma_f32 v1, v68, v193, v195
	v_add_f32_e32 v192, v0, v132
	v_add_f32_e32 v193, v1, v133
	s_waitcnt lgkmcnt(12)
	v_mul_f32_e32 v194, v69, v193
	v_mul_f32_e32 v195, v69, v192
	v_fma_f32 v0, v68, v192, -v194
	v_fma_f32 v1, v68, v193, v195
	v_add_f32_e32 v192, v0, v134
	v_add_f32_e32 v193, v1, v135
	s_waitcnt lgkmcnt(11)
	v_mul_f32_e32 v194, v69, v193
	v_mul_f32_e32 v195, v69, v192
	v_fma_f32 v0, v68, v192, -v194
	v_fma_f32 v1, v68, v193, v195
	v_add_f32_e32 v192, v0, v136
	v_add_f32_e32 v193, v1, v137
	s_waitcnt lgkmcnt(10)
	v_mul_f32_e32 v194, v69, v193
	v_mul_f32_e32 v195, v69, v192
	v_fma_f32 v0, v68, v192, -v194
	v_fma_f32 v1, v68, v193, v195
	v_add_f32_e32 v192, v0, v138
	v_add_f32_e32 v193, v1, v139
	s_waitcnt lgkmcnt(9)
	v_mul_f32_e32 v194, v69, v193
	v_mul_f32_e32 v195, v69, v192
	v_fma_f32 v0, v68, v192, -v194
	v_fma_f32 v1, v68, v193, v195
	v_add_f32_e32 v192, v0, v140
	v_add_f32_e32 v193, v1, v141
	s_waitcnt lgkmcnt(8)
	v_mul_f32_e32 v194, v69, v193
	v_mul_f32_e32 v195, v69, v192
	v_fma_f32 v0, v68, v192, -v194
	v_fma_f32 v1, v68, v193, v195
	v_add_f32_e32 v192, v0, v142
	v_add_f32_e32 v193, v1, v143
	s_waitcnt lgkmcnt(7)
	v_mul_f32_e32 v194, v69, v193
	v_mul_f32_e32 v195, v69, v192
	v_fma_f32 v0, v68, v192, -v194
	v_fma_f32 v1, v68, v193, v195
	v_add_f32_e32 v192, v0, v144
	v_add_f32_e32 v193, v1, v145
	s_waitcnt lgkmcnt(6)
	v_mul_f32_e32 v194, v69, v193
	v_mul_f32_e32 v195, v69, v192
	v_fma_f32 v0, v68, v192, -v194
	v_fma_f32 v1, v68, v193, v195
	v_add_f32_e32 v192, v0, v146
	v_add_f32_e32 v193, v1, v147
	s_waitcnt lgkmcnt(5)
	v_mul_f32_e32 v194, v69, v193
	v_mul_f32_e32 v195, v69, v192
	v_fma_f32 v0, v68, v192, -v194
	v_fma_f32 v1, v68, v193, v195
	v_add_f32_e32 v192, v0, v148
	v_add_f32_e32 v193, v1, v149
	s_waitcnt lgkmcnt(4)
	v_mul_f32_e32 v194, v69, v193
	v_mul_f32_e32 v195, v69, v192
	v_fma_f32 v0, v68, v192, -v194
	v_fma_f32 v1, v68, v193, v195
	v_add_f32_e32 v192, v0, v150
	v_add_f32_e32 v193, v1, v151
	s_waitcnt lgkmcnt(3)
	v_mul_f32_e32 v194, v69, v193
	v_mul_f32_e32 v195, v69, v192
	v_fma_f32 v0, v68, v192, -v194
	v_fma_f32 v1, v68, v193, v195
	v_add_f32_e32 v192, v0, v152
	v_add_f32_e32 v193, v1, v153
	s_waitcnt lgkmcnt(2)
	v_mul_f32_e32 v194, v69, v193
	v_mul_f32_e32 v195, v69, v192
	v_fma_f32 v0, v68, v192, -v194
	v_fma_f32 v1, v68, v193, v195
	v_add_f32_e32 v192, v0, v154
	v_add_f32_e32 v193, v1, v155
	s_waitcnt lgkmcnt(1)
	v_mul_f32_e32 v194, v69, v193
	v_mul_f32_e32 v195, v69, v192
	v_fma_f32 v0, v68, v192, -v194
	v_fma_f32 v1, v68, v193, v195
	v_add_f32_e32 v192, v0, v156
	v_add_f32_e32 v193, v1, v157
	s_waitcnt lgkmcnt(0)
	v_mul_f32_e32 v194, v69, v193
	v_mul_f32_e32 v195, v69, v192
	v_fma_f32 v0, v68, v192, -v194
	v_fma_f32 v1, v68, v193, v195
	v_add_f32_e32 v192, v0, v158
	v_add_f32_e32 v193, v1, v159
.Ls5l_sdone0:
	global_store_dwordx2 v10, v[192:193], s[50:51]
	s_nop 1
	s_add_u32 s43, s41, 4096
	s_lshr_b32 s98, s43, 5
	s_bfe_u32 s99, s43, 0x40001
	s_and_b32 s54, s43, 1
	s_cmpk_lt_u32 s98, 0x80
	s_cbranch_scc1 .Ls5l_ctx2
	s_sub_u32 s100, s98, 0x80
	s_lshr_b32 s101, s100, 5
	s_and_b32 s100, s100, 31
	s_lshl_b32 s101, s101, 10
	s_lshl_b32 s100, s100, 1
	s_add_u32 s100, s100, s101
	s_add_u32 s100, s100, 0x1000
	s_mov_b32 s52, 0x91000
	s_movk_i32 s53, 0x2440
	s_branch .Ls5l_rows2

.Ls5l_rows2:
	s_mul_i32 s100, s100, 0x2440
	s_lshl_b32 s101, s99, 6
	s_add_u32 s100, s100, s101
	s_add_u32 s100, s100, 0x3a26040
	s_add_u32 s44, s96, s100
	s_addc_u32 s45, s97, 0
	s_lshl_b32 s101, s36, 1
	s_add_u32 s101, s101, s54
	s_lshl_b32 s101, s101, 4
	s_add_u32 s101, s101, s99
	s_lshl_b32 s100, s101, 12
	s_add_u32 s100, s100, 0xd1c4000
	s_add_u32 s46, s96, s100
	s_addc_u32 s47, s97, 0
	s_lshl_b32 s100, s101, 11
	s_add_u32 s100, s100, 0xd1a4000
	s_add_u32 s48, s96, s100
	s_addc_u32 s49, s97, 0
	s_lshl_b32 s100, s98, 4
	s_add_u32 s100, s100, s99
	s_lshl_b32 s100, s100, 1
	s_add_u32 s100, s100, s54
	s_lshl_b32 s100, s100, 9
	s_add_u32 s100, s100, 0xcba4000
	s_add_u32 s50, s96, s100
	s_addc_u32 s51, s97, 0
	v_mul_lo_u32 v11, v4, s52
	v_lshl_add_u32 v11, v5, 5, v11
	v_add_u32_e32 v12, s53, v11
	v_mov_b32_e32 v20, 0
	v_mov_b32_e32 v21, 0
	v_mov_b32_e32 v22, 0
	v_mov_b32_e32 v23, 0
	v_mov_b32_e32 v24, 0
	v_mov_b32_e32 v25, 0
	v_mov_b32_e32 v26, 0
	v_mov_b32_e32 v27, 0
	v_mov_b32_e32 v28, 0
	v_mov_b32_e32 v29, 0
	v_mov_b32_e32 v30, 0
	v_mov_b32_e32 v31, 0
	v_mov_b32_e32 v32, 0
	v_mov_b32_e32 v33, 0
	v_mov_b32_e32 v34, 0
	v_mov_b32_e32 v35, 0
	s_mov_b64 s[38:39], exec
	s_mov_b32 exec_lo, -1
	s_mov_b32 exec_hi, 0
	global_load_dwordx4 v[20:23], v11, s[44:45]
	global_load_dwordx4 v[24:27], v11, s[44:45] offset:16
	global_load_dwordx4 v[28:31], v12, s[44:45]
	global_load_dwordx4 v[32:35], v12, s[44:45] offset:16
	s_mov_b64 exec, s[38:39]
	global_load_dwordx4 v[36:39], v8, s[46:47]
	global_load_dwordx4 v[40:43], v8, s[46:47] offset:512
	global_load_dwordx4 v[44:47], v8, s[46:47] offset:1024
	global_load_dwordx4 v[48:51], v8, s[46:47] offset:1536
	global_load_dwordx4 v[52:55], v8, s[46:47] offset:2048
	global_load_dwordx4 v[56:59], v8, s[46:47] offset:2560
	global_load_dwordx4 v[60:63], v8, s[46:47] offset:3072
	global_load_dwordx4 v[64:67], v8, s[46:47] offset:3584
	global_load_dwordx2 v[68:69], v9, s[48:49]
	s_waitcnt vmcnt(14)
	v_cvt_pk_bf16_f32 v120, v70, v71
	v_cvt_pk_bf16_f32 v121, v72, v73
	v_cvt_pk_bf16_f32 v122, v74, v75
	v_cvt_pk_bf16_f32 v123, v76, v77
	v_cvt_pk_bf16_f32 v124, v78, v79
	v_cvt_pk_bf16_f32 v125, v80, v81
	v_cvt_pk_bf16_f32 v126, v82, v83
	v_cvt_pk_bf16_f32 v127, v84, v85
	s_nop 1
	v_mfma_f32_16x16x32_bf16 v[128:131], v[120:123], v[86:89], 0
	v_mfma_f32_16x16x32_bf16 v[132:135], v[124:127], v[86:89], 0
	v_mfma_f32_16x16x32_bf16 v[136:139], v[120:123], v[90:93], 0
	v_mfma_f32_16x16x32_bf16 v[140:143], v[124:127], v[90:93], 0
	v_mfma_f32_16x16x32_bf16 v[144:147], v[120:123], v[94:97], 0
	v_mfma_f32_16x16x32_bf16 v[148:151], v[124:127], v[94:97], 0
	v_mfma_f32_16x16x32_bf16 v[152:155], v[120:123], v[98:101], 0
	v_mfma_f32_16x16x32_bf16 v[156:159], v[124:127], v[98:101], 0
	v_mfma_f32_16x16x32_bf16 v[160:163], v[120:123], v[102:105], 0
	v_mfma_f32_16x16x32_bf16 v[164:167], v[124:127], v[102:105], 0
	v_mfma_f32_16x16x32_bf16 v[168:171], v[120:123], v[106:109], 0
	v_mfma_f32_16x16x32_bf16 v[172:175], v[124:127], v[106:109], 0
	v_mfma_f32_16x16x32_bf16 v[176:179], v[120:123], v[110:113], 0
	v_mfma_f32_16x16x32_bf16 v[180:183], v[124:127], v[110:113], 0
	v_mfma_f32_16x16x32_bf16 v[184:187], v[120:123], v[114:117], 0
	v_mfma_f32_16x16x32_bf16 v[188:191], v[124:127], v[114:117], 0
	ds_write_b32 v6, v128 offset:0
	ds_write_b32 v6, v129 offset:528
	ds_write_b32 v6, v130 offset:1056
	ds_write_b32 v6, v131 offset:1584
	ds_write_b32 v6, v132 offset:8448
	ds_write_b32 v6, v133 offset:8976
	ds_write_b32 v6, v134 offset:9504
	ds_write_b32 v6, v135 offset:10032
	ds_write_b32 v6, v136 offset:64
	ds_write_b32 v6, v137 offset:592
	ds_write_b32 v6, v138 offset:1120
	ds_write_b32 v6, v139 offset:1648
	ds_write_b32 v6, v140 offset:8512
	ds_write_b32 v6, v141 offset:9040
	ds_write_b32 v6, v142 offset:9568
	ds_write_b32 v6, v143 offset:10096
	ds_write_b32 v6, v144 offset:128
	ds_write_b32 v6, v145 offset:656
	ds_write_b32 v6, v146 offset:1184
	ds_write_b32 v6, v147 offset:1712
	ds_write_b32 v6, v148 offset:8576
	ds_write_b32 v6, v149 offset:9104
	ds_write_b32 v6, v150 offset:9632
	ds_write_b32 v6, v151 offset:10160
	ds_write_b32 v6, v152 offset:192
	ds_write_b32 v6, v153 offset:720
	ds_write_b32 v6, v154 offset:1248
	ds_write_b32 v6, v155 offset:1776
	ds_write_b32 v6, v156 offset:8640
	ds_write_b32 v6, v157 offset:9168
	ds_write_b32 v6, v158 offset:9696
	ds_write_b32 v6, v159 offset:10224
	ds_write_b32 v6, v160 offset:256
	ds_write_b32 v6, v161 offset:784
	ds_write_b32 v6, v162 offset:1312
	ds_write_b32 v6, v163 offset:1840
	ds_write_b32 v6, v164 offset:8704
	ds_write_b32 v6, v165 offset:9232
	ds_write_b32 v6, v166 offset:9760
	ds_write_b32 v6, v167 offset:10288
	ds_write_b32 v6, v168 offset:320
	ds_write_b32 v6, v169 offset:848
	ds_write_b32 v6, v170 offset:1376
	ds_write_b32 v6, v171 offset:1904
	ds_write_b32 v6, v172 offset:8768
	ds_write_b32 v6, v173 offset:9296
	ds_write_b32 v6, v174 offset:9824
	ds_write_b32 v6, v175 offset:10352
	ds_write_b32 v6, v176 offset:384
	ds_write_b32 v6, v177 offset:912
	ds_write_b32 v6, v178 offset:1440
	ds_write_b32 v6, v179 offset:1968
	ds_write_b32 v6, v180 offset:8832
	ds_write_b32 v6, v181 offset:9360
	ds_write_b32 v6, v182 offset:9888
	ds_write_b32 v6, v183 offset:10416
	ds_write_b32 v6, v184 offset:448
	ds_write_b32 v6, v185 offset:976
	ds_write_b32 v6, v186 offset:1504
	ds_write_b32 v6, v187 offset:2032
	s_nop 4
	ds_write_b32 v6, v188 offset:8896
	ds_write_b32 v6, v189 offset:9424
	ds_write_b32 v6, v190 offset:9952
	ds_write_b32 v6, v191 offset:10480
	v_mov_b32_e32 v192, 0
	v_mov_b32_e32 v193, 0
	s_waitcnt lgkmcnt(0)
	s_cmp_eq_u32 s55, 0
	s_cbranch_scc0 .Ls5l_bwd1
	ds_read_b64 v[128:129], v7 offset:0
	ds_read_b64 v[130:131], v7 offset:528
	ds_read_b64 v[132:133], v7 offset:1056
	ds_read_b64 v[134:135], v7 offset:1584
	ds_read_b64 v[136:137], v7 offset:2112
	ds_read_b64 v[138:139], v7 offset:2640
	ds_read_b64 v[140:141], v7 offset:3168
	ds_read_b64 v[142:143], v7 offset:3696
	ds_read_b64 v[144:145], v7 offset:4224
	ds_read_b64 v[146:147], v7 offset:4752
	ds_read_b64 v[148:149], v7 offset:5280
	ds_read_b64 v[150:151], v7 offset:5808
	ds_read_b64 v[152:153], v7 offset:6336
	ds_read_b64 v[154:155], v7 offset:6864
	ds_read_b64 v[156:157], v7 offset:7392
	ds_read_b64 v[158:159], v7 offset:7920
	s_waitcnt lgkmcnt(15)
	v_mul_f32_e32 v194, v119, v193
	v_mul_f32_e32 v195, v119, v192
	v_fma_f32 v0, v118, v192, -v194
	v_fma_f32 v1, v118, v193, v195
	v_add_f32_e32 v192, v0, v128
	v_add_f32_e32 v193, v1, v129
	s_waitcnt lgkmcnt(14)
	v_mul_f32_e32 v194, v119, v193
	v_mul_f32_e32 v195, v119, v192
	v_fma_f32 v0, v118, v192, -v194
	v_fma_f32 v1, v118, v193, v195
	v_add_f32_e32 v192, v0, v130
	v_add_f32_e32 v193, v1, v131
	s_waitcnt lgkmcnt(13)
	v_mul_f32_e32 v194, v119, v193
	v_mul_f32_e32 v195, v119, v192
	v_fma_f32 v0, v118, v192, -v194
	v_fma_f32 v1, v118, v193, v195
	v_add_f32_e32 v192, v0, v132
	v_add_f32_e32 v193, v1, v133
	s_waitcnt lgkmcnt(12)
	v_mul_f32_e32 v194, v119, v193
	v_mul_f32_e32 v195, v119, v192
	v_fma_f32 v0, v118, v192, -v194
	v_fma_f32 v1, v118, v193, v195
	v_add_f32_e32 v192, v0, v134
	v_add_f32_e32 v193, v1, v135
	s_waitcnt lgkmcnt(11)
	v_mul_f32_e32 v194, v119, v193
	v_mul_f32_e32 v195, v119, v192
	v_fma_f32 v0, v118, v192, -v194
	v_fma_f32 v1, v118, v193, v195
	v_add_f32_e32 v192, v0, v136
	v_add_f32_e32 v193, v1, v137
	s_waitcnt lgkmcnt(10)
	v_mul_f32_e32 v194, v119, v193
	v_mul_f32_e32 v195, v119, v192
	v_fma_f32 v0, v118, v192, -v194
	v_fma_f32 v1, v118, v193, v195
	v_add_f32_e32 v192, v0, v138
	v_add_f32_e32 v193, v1, v139
	s_waitcnt lgkmcnt(9)
	v_mul_f32_e32 v194, v119, v193
	v_mul_f32_e32 v195, v119, v192
	v_fma_f32 v0, v118, v192, -v194
	v_fma_f32 v1, v118, v193, v195
	v_add_f32_e32 v192, v0, v140
	v_add_f32_e32 v193, v1, v141
	s_waitcnt lgkmcnt(8)
	v_mul_f32_e32 v194, v119, v193
	v_mul_f32_e32 v195, v119, v192
	v_fma_f32 v0, v118, v192, -v194
	v_fma_f32 v1, v118, v193, v195
	v_add_f32_e32 v192, v0, v142
	v_add_f32_e32 v193, v1, v143
	ds_read_b64 v[128:129], v7 offset:8448
	ds_read_b64 v[130:131], v7 offset:8976
	ds_read_b64 v[132:133], v7 offset:9504
	ds_read_b64 v[134:135], v7 offset:10032
	ds_read_b64 v[136:137], v7 offset:10560
	ds_read_b64 v[138:139], v7 offset:11088
	ds_read_b64 v[140:141], v7 offset:11616
	ds_read_b64 v[142:143], v7 offset:12144
	s_waitcnt lgkmcnt(15)
	v_mul_f32_e32 v194, v119, v193
	v_mul_f32_e32 v195, v119, v192
	v_fma_f32 v0, v118, v192, -v194
	v_fma_f32 v1, v118, v193, v195
	v_add_f32_e32 v192, v0, v144
	v_add_f32_e32 v193, v1, v145
	s_waitcnt lgkmcnt(14)
	v_mul_f32_e32 v194, v119, v193
	v_mul_f32_e32 v195, v119, v192
	v_fma_f32 v0, v118, v192, -v194
	v_fma_f32 v1, v118, v193, v195
	v_add_f32_e32 v192, v0, v146
	v_add_f32_e32 v193, v1, v147
	s_waitcnt lgkmcnt(13)
	v_mul_f32_e32 v194, v119, v193
	v_mul_f32_e32 v195, v119, v192
	v_fma_f32 v0, v118, v192, -v194
	v_fma_f32 v1, v118, v193, v195
	v_add_f32_e32 v192, v0, v148
	v_add_f32_e32 v193, v1, v149
	s_waitcnt lgkmcnt(12)
	v_mul_f32_e32 v194, v119, v193
	v_mul_f32_e32 v195, v119, v192
	v_fma_f32 v0, v118, v192, -v194
	v_fma_f32 v1, v118, v193, v195
	v_add_f32_e32 v192, v0, v150
	v_add_f32_e32 v193, v1, v151
	s_waitcnt lgkmcnt(11)
	v_mul_f32_e32 v194, v119, v193
	v_mul_f32_e32 v195, v119, v192
	v_fma_f32 v0, v118, v192, -v194
	v_fma_f32 v1, v118, v193, v195
	v_add_f32_e32 v192, v0, v152
	v_add_f32_e32 v193, v1, v153
	s_waitcnt lgkmcnt(10)
	v_mul_f32_e32 v194, v119, v193
	v_mul_f32_e32 v195, v119, v192
	v_fma_f32 v0, v118, v192, -v194
	v_fma_f32 v1, v118, v193, v195
	v_add_f32_e32 v192, v0, v154
	v_add_f32_e32 v193, v1, v155
	s_waitcnt lgkmcnt(9)
	v_mul_f32_e32 v194, v119, v193
	v_mul_f32_e32 v195, v119, v192
	v_fma_f32 v0, v118, v192, -v194
	v_fma_f32 v1, v118, v193, v195
	v_add_f32_e32 v192, v0, v156
	v_add_f32_e32 v193, v1, v157
	s_waitcnt lgkmcnt(8)
	v_mul_f32_e32 v194, v119, v193
	v_mul_f32_e32 v195, v119, v192
	v_fma_f32 v0, v118, v192, -v194
	v_fma_f32 v1, v118, v193, v195
	v_add_f32_e32 v192, v0, v158
	v_add_f32_e32 v193, v1, v159
	ds_read_b64 v[144:145], v7 offset:12672
	ds_read_b64 v[146:147], v7 offset:13200
	ds_read_b64 v[148:149], v7 offset:13728
	ds_read_b64 v[150:151], v7 offset:14256
	ds_read_b64 v[152:153], v7 offset:14784
	ds_read_b64 v[154:155], v7 offset:15312
	ds_read_b64 v[156:157], v7 offset:15840
	ds_read_b64 v[158:159], v7 offset:16368
	s_waitcnt lgkmcnt(15)
	v_mul_f32_e32 v194, v119, v193
	v_mul_f32_e32 v195, v119, v192
	v_fma_f32 v0, v118, v192, -v194
	v_fma_f32 v1, v118, v193, v195
	v_add_f32_e32 v192, v0, v128
	v_add_f32_e32 v193, v1, v129
	s_waitcnt lgkmcnt(14)
	v_mul_f32_e32 v194, v119, v193
	v_mul_f32_e32 v195, v119, v192
	v_fma_f32 v0, v118, v192, -v194
	v_fma_f32 v1, v118, v193, v195
	v_add_f32_e32 v192, v0, v130
	v_add_f32_e32 v193, v1, v131
	s_waitcnt lgkmcnt(13)
	v_mul_f32_e32 v194, v119, v193
	v_mul_f32_e32 v195, v119, v192
	v_fma_f32 v0, v118, v192, -v194
	v_fma_f32 v1, v118, v193, v195
	v_add_f32_e32 v192, v0, v132
	v_add_f32_e32 v193, v1, v133
	s_waitcnt lgkmcnt(12)
	v_mul_f32_e32 v194, v119, v193
	v_mul_f32_e32 v195, v119, v192
	v_fma_f32 v0, v118, v192, -v194
	v_fma_f32 v1, v118, v193, v195
	v_add_f32_e32 v192, v0, v134
	v_add_f32_e32 v193, v1, v135
	s_waitcnt lgkmcnt(11)
	v_mul_f32_e32 v194, v119, v193
	v_mul_f32_e32 v195, v119, v192
	v_fma_f32 v0, v118, v192, -v194
	v_fma_f32 v1, v118, v193, v195
	v_add_f32_e32 v192, v0, v136
	v_add_f32_e32 v193, v1, v137
	s_waitcnt lgkmcnt(10)
	v_mul_f32_e32 v194, v119, v193
	v_mul_f32_e32 v195, v119, v192
	v_fma_f32 v0, v118, v192, -v194
	v_fma_f32 v1, v118, v193, v195
	v_add_f32_e32 v192, v0, v138
	v_add_f32_e32 v193, v1, v139
	s_waitcnt lgkmcnt(9)
	v_mul_f32_e32 v194, v119, v193
	v_mul_f32_e32 v195, v119, v192
	v_fma_f32 v0, v118, v192, -v194
	v_fma_f32 v1, v118, v193, v195
	v_add_f32_e32 v192, v0, v140
	v_add_f32_e32 v193, v1, v141
	s_waitcnt lgkmcnt(8)
	v_mul_f32_e32 v194, v119, v193
	v_mul_f32_e32 v195, v119, v192
	v_fma_f32 v0, v118, v192, -v194
	v_fma_f32 v1, v118, v193, v195
	v_add_f32_e32 v192, v0, v142
	v_add_f32_e32 v193, v1, v143
	s_waitcnt lgkmcnt(7)
	v_mul_f32_e32 v194, v119, v193
	v_mul_f32_e32 v195, v119, v192
	v_fma_f32 v0, v118, v192, -v194
	v_fma_f32 v1, v118, v193, v195
	v_add_f32_e32 v192, v0, v144
	v_add_f32_e32 v193, v1, v145
	s_waitcnt lgkmcnt(6)
	v_mul_f32_e32 v194, v119, v193
	v_mul_f32_e32 v195, v119, v192
	v_fma_f32 v0, v118, v192, -v194
	v_fma_f32 v1, v118, v193, v195
	v_add_f32_e32 v192, v0, v146
	v_add_f32_e32 v193, v1, v147
	s_waitcnt lgkmcnt(5)
	v_mul_f32_e32 v194, v119, v193
	v_mul_f32_e32 v195, v119, v192
	v_fma_f32 v0, v118, v192, -v194
	v_fma_f32 v1, v118, v193, v195
	v_add_f32_e32 v192, v0, v148
	v_add_f32_e32 v193, v1, v149
	s_waitcnt lgkmcnt(4)
	v_mul_f32_e32 v194, v119, v193
	v_mul_f32_e32 v195, v119, v192
	v_fma_f32 v0, v118, v192, -v194
	v_fma_f32 v1, v118, v193, v195
	v_add_f32_e32 v192, v0, v150
	v_add_f32_e32 v193, v1, v151
	s_waitcnt lgkmcnt(3)
	v_mul_f32_e32 v194, v119, v193
	v_mul_f32_e32 v195, v119, v192
	v_fma_f32 v0, v118, v192, -v194
	v_fma_f32 v1, v118, v193, v195
	v_add_f32_e32 v192, v0, v152
	v_add_f32_e32 v193, v1, v153
	s_waitcnt lgkmcnt(2)
	v_mul_f32_e32 v194, v119, v193
	v_mul_f32_e32 v195, v119, v192
	v_fma_f32 v0, v118, v192, -v194
	v_fma_f32 v1, v118, v193, v195
	v_add_f32_e32 v192, v0, v154
	v_add_f32_e32 v193, v1, v155
	s_waitcnt lgkmcnt(1)
	v_mul_f32_e32 v194, v119, v193
	v_mul_f32_e32 v195, v119, v192
	v_fma_f32 v0, v118, v192, -v194
	v_fma_f32 v1, v118, v193, v195
	v_add_f32_e32 v192, v0, v156
	v_add_f32_e32 v193, v1, v157
	s_waitcnt lgkmcnt(0)
	v_mul_f32_e32 v194, v119, v193
	v_mul_f32_e32 v195, v119, v192
	v_fma_f32 v0, v118, v192, -v194
	v_fma_f32 v1, v118, v193, v195
	v_add_f32_e32 v192, v0, v158
	v_add_f32_e32 v193, v1, v159
	s_branch .Ls5l_sdone1
.Ls5l_bwd1:
	ds_read_b64 v[128:129], v7 offset:16368
	ds_read_b64 v[130:131], v7 offset:15840
	ds_read_b64 v[132:133], v7 offset:15312
	ds_read_b64 v[134:135], v7 offset:14784
	ds_read_b64 v[136:137], v7 offset:14256
	ds_read_b64 v[138:139], v7 offset:13728
	ds_read_b64 v[140:141], v7 offset:13200
	ds_read_b64 v[142:143], v7 offset:12672
	ds_read_b64 v[144:145], v7 offset:12144
	ds_read_b64 v[146:147], v7 offset:11616
	ds_read_b64 v[148:149], v7 offset:11088
	ds_read_b64 v[150:151], v7 offset:10560
	ds_read_b64 v[152:153], v7 offset:10032
	ds_read_b64 v[154:155], v7 offset:9504
	ds_read_b64 v[156:157], v7 offset:8976
	ds_read_b64 v[158:159], v7 offset:8448
	s_waitcnt lgkmcnt(15)
	v_mul_f32_e32 v194, v119, v193
	v_mul_f32_e32 v195, v119, v192
	v_fma_f32 v0, v118, v192, -v194
	v_fma_f32 v1, v118, v193, v195
	v_add_f32_e32 v192, v0, v128
	v_add_f32_e32 v193, v1, v129
	s_waitcnt lgkmcnt(14)
	v_mul_f32_e32 v194, v119, v193
	v_mul_f32_e32 v195, v119, v192
	v_fma_f32 v0, v118, v192, -v194
	v_fma_f32 v1, v118, v193, v195
	v_add_f32_e32 v192, v0, v130
	v_add_f32_e32 v193, v1, v131
	s_waitcnt lgkmcnt(13)
	v_mul_f32_e32 v194, v119, v193
	v_mul_f32_e32 v195, v119, v192
	v_fma_f32 v0, v118, v192, -v194
	v_fma_f32 v1, v118, v193, v195
	v_add_f32_e32 v192, v0, v132
	v_add_f32_e32 v193, v1, v133
	s_waitcnt lgkmcnt(12)
	v_mul_f32_e32 v194, v119, v193
	v_mul_f32_e32 v195, v119, v192
	v_fma_f32 v0, v118, v192, -v194
	v_fma_f32 v1, v118, v193, v195
	v_add_f32_e32 v192, v0, v134
	v_add_f32_e32 v193, v1, v135
	s_waitcnt lgkmcnt(11)
	v_mul_f32_e32 v194, v119, v193
	v_mul_f32_e32 v195, v119, v192
	v_fma_f32 v0, v118, v192, -v194
	v_fma_f32 v1, v118, v193, v195
	v_add_f32_e32 v192, v0, v136
	v_add_f32_e32 v193, v1, v137
	s_waitcnt lgkmcnt(10)
	v_mul_f32_e32 v194, v119, v193
	v_mul_f32_e32 v195, v119, v192
	v_fma_f32 v0, v118, v192, -v194
	v_fma_f32 v1, v118, v193, v195
	v_add_f32_e32 v192, v0, v138
	v_add_f32_e32 v193, v1, v139
	s_waitcnt lgkmcnt(9)
	v_mul_f32_e32 v194, v119, v193
	v_mul_f32_e32 v195, v119, v192
	v_fma_f32 v0, v118, v192, -v194
	v_fma_f32 v1, v118, v193, v195
	v_add_f32_e32 v192, v0, v140
	v_add_f32_e32 v193, v1, v141
	s_waitcnt lgkmcnt(8)
	v_mul_f32_e32 v194, v119, v193
	v_mul_f32_e32 v195, v119, v192
	v_fma_f32 v0, v118, v192, -v194
	v_fma_f32 v1, v118, v193, v195
	v_add_f32_e32 v192, v0, v142
	v_add_f32_e32 v193, v1, v143
	ds_read_b64 v[128:129], v7 offset:7920
	ds_read_b64 v[130:131], v7 offset:7392
	ds_read_b64 v[132:133], v7 offset:6864
	ds_read_b64 v[134:135], v7 offset:6336
	ds_read_b64 v[136:137], v7 offset:5808
	ds_read_b64 v[138:139], v7 offset:5280
	ds_read_b64 v[140:141], v7 offset:4752
	ds_read_b64 v[142:143], v7 offset:4224
	s_waitcnt lgkmcnt(15)
	v_mul_f32_e32 v194, v119, v193
	v_mul_f32_e32 v195, v119, v192
	v_fma_f32 v0, v118, v192, -v194
	v_fma_f32 v1, v118, v193, v195
	v_add_f32_e32 v192, v0, v144
	v_add_f32_e32 v193, v1, v145
	s_waitcnt lgkmcnt(14)
	v_mul_f32_e32 v194, v119, v193
	v_mul_f32_e32 v195, v119, v192
	v_fma_f32 v0, v118, v192, -v194
	v_fma_f32 v1, v118, v193, v195
	v_add_f32_e32 v192, v0, v146
	v_add_f32_e32 v193, v1, v147
	s_waitcnt lgkmcnt(13)
	v_mul_f32_e32 v194, v119, v193
	v_mul_f32_e32 v195, v119, v192
	v_fma_f32 v0, v118, v192, -v194
	v_fma_f32 v1, v118, v193, v195
	v_add_f32_e32 v192, v0, v148
	v_add_f32_e32 v193, v1, v149
	s_waitcnt lgkmcnt(12)
	v_mul_f32_e32 v194, v119, v193
	v_mul_f32_e32 v195, v119, v192
	v_fma_f32 v0, v118, v192, -v194
	v_fma_f32 v1, v118, v193, v195
	v_add_f32_e32 v192, v0, v150
	v_add_f32_e32 v193, v1, v151
	s_waitcnt lgkmcnt(11)
	v_mul_f32_e32 v194, v119, v193
	v_mul_f32_e32 v195, v119, v192
	v_fma_f32 v0, v118, v192, -v194
	v_fma_f32 v1, v118, v193, v195
	v_add_f32_e32 v192, v0, v152
	v_add_f32_e32 v193, v1, v153
	s_waitcnt lgkmcnt(10)
	v_mul_f32_e32 v194, v119, v193
	v_mul_f32_e32 v195, v119, v192
	v_fma_f32 v0, v118, v192, -v194
	v_fma_f32 v1, v118, v193, v195
	v_add_f32_e32 v192, v0, v154
	v_add_f32_e32 v193, v1, v155
	s_waitcnt lgkmcnt(9)
	v_mul_f32_e32 v194, v119, v193
	v_mul_f32_e32 v195, v119, v192
	v_fma_f32 v0, v118, v192, -v194
	v_fma_f32 v1, v118, v193, v195
	v_add_f32_e32 v192, v0, v156
	v_add_f32_e32 v193, v1, v157
	s_waitcnt lgkmcnt(8)
	v_mul_f32_e32 v194, v119, v193
	v_mul_f32_e32 v195, v119, v192
	v_fma_f32 v0, v118, v192, -v194
	v_fma_f32 v1, v118, v193, v195
	v_add_f32_e32 v192, v0, v158
	v_add_f32_e32 v193, v1, v159
	ds_read_b64 v[144:145], v7 offset:3696
	ds_read_b64 v[146:147], v7 offset:3168
	ds_read_b64 v[148:149], v7 offset:2640
	ds_read_b64 v[150:151], v7 offset:2112
	ds_read_b64 v[152:153], v7 offset:1584
	ds_read_b64 v[154:155], v7 offset:1056
	ds_read_b64 v[156:157], v7 offset:528
	ds_read_b64 v[158:159], v7 offset:0
	s_waitcnt lgkmcnt(15)
	v_mul_f32_e32 v194, v119, v193
	v_mul_f32_e32 v195, v119, v192
	v_fma_f32 v0, v118, v192, -v194
	v_fma_f32 v1, v118, v193, v195
	v_add_f32_e32 v192, v0, v128
	v_add_f32_e32 v193, v1, v129
	s_waitcnt lgkmcnt(14)
	v_mul_f32_e32 v194, v119, v193
	v_mul_f32_e32 v195, v119, v192
	v_fma_f32 v0, v118, v192, -v194
	v_fma_f32 v1, v118, v193, v195
	v_add_f32_e32 v192, v0, v130
	v_add_f32_e32 v193, v1, v131
	s_waitcnt lgkmcnt(13)
	v_mul_f32_e32 v194, v119, v193
	v_mul_f32_e32 v195, v119, v192
	v_fma_f32 v0, v118, v192, -v194
	v_fma_f32 v1, v118, v193, v195
	v_add_f32_e32 v192, v0, v132
	v_add_f32_e32 v193, v1, v133
	s_waitcnt lgkmcnt(12)
	v_mul_f32_e32 v194, v119, v193
	v_mul_f32_e32 v195, v119, v192
	v_fma_f32 v0, v118, v192, -v194
	v_fma_f32 v1, v118, v193, v195
	v_add_f32_e32 v192, v0, v134
	v_add_f32_e32 v193, v1, v135
	s_waitcnt lgkmcnt(11)
	v_mul_f32_e32 v194, v119, v193
	v_mul_f32_e32 v195, v119, v192
	v_fma_f32 v0, v118, v192, -v194
	v_fma_f32 v1, v118, v193, v195
	v_add_f32_e32 v192, v0, v136
	v_add_f32_e32 v193, v1, v137
	s_waitcnt lgkmcnt(10)
	v_mul_f32_e32 v194, v119, v193
	v_mul_f32_e32 v195, v119, v192
	v_fma_f32 v0, v118, v192, -v194
	v_fma_f32 v1, v118, v193, v195
	v_add_f32_e32 v192, v0, v138
	v_add_f32_e32 v193, v1, v139
	s_waitcnt lgkmcnt(9)
	v_mul_f32_e32 v194, v119, v193
	v_mul_f32_e32 v195, v119, v192
	v_fma_f32 v0, v118, v192, -v194
	v_fma_f32 v1, v118, v193, v195
	v_add_f32_e32 v192, v0, v140
	v_add_f32_e32 v193, v1, v141
	s_waitcnt lgkmcnt(8)
	v_mul_f32_e32 v194, v119, v193
	v_mul_f32_e32 v195, v119, v192
	v_fma_f32 v0, v118, v192, -v194
	v_fma_f32 v1, v118, v193, v195
	v_add_f32_e32 v192, v0, v142
	v_add_f32_e32 v193, v1, v143
	s_waitcnt lgkmcnt(7)
	v_mul_f32_e32 v194, v119, v193
	v_mul_f32_e32 v195, v119, v192
	v_fma_f32 v0, v118, v192, -v194
	v_fma_f32 v1, v118, v193, v195
	v_add_f32_e32 v192, v0, v144
	v_add_f32_e32 v193, v1, v145
	s_waitcnt lgkmcnt(6)
	v_mul_f32_e32 v194, v119, v193
	v_mul_f32_e32 v195, v119, v192
	v_fma_f32 v0, v118, v192, -v194
	v_fma_f32 v1, v118, v193, v195
	v_add_f32_e32 v192, v0, v146
	v_add_f32_e32 v193, v1, v147
	s_waitcnt lgkmcnt(5)
	v_mul_f32_e32 v194, v119, v193
	v_mul_f32_e32 v195, v119, v192
	v_fma_f32 v0, v118, v192, -v194
	v_fma_f32 v1, v118, v193, v195
	v_add_f32_e32 v192, v0, v148
	v_add_f32_e32 v193, v1, v149
	s_waitcnt lgkmcnt(4)
	v_mul_f32_e32 v194, v119, v193
	v_mul_f32_e32 v195, v119, v192
	v_fma_f32 v0, v118, v192, -v194
	v_fma_f32 v1, v118, v193, v195
	v_add_f32_e32 v192, v0, v150
	v_add_f32_e32 v193, v1, v151
	s_waitcnt lgkmcnt(3)
	v_mul_f32_e32 v194, v119, v193
	v_mul_f32_e32 v195, v119, v192
	v_fma_f32 v0, v118, v192, -v194
	v_fma_f32 v1, v118, v193, v195
	v_add_f32_e32 v192, v0, v152
	v_add_f32_e32 v193, v1, v153
	s_waitcnt lgkmcnt(2)
	v_mul_f32_e32 v194, v119, v193
	v_mul_f32_e32 v195, v119, v192
	v_fma_f32 v0, v118, v192, -v194
	v_fma_f32 v1, v118, v193, v195
	v_add_f32_e32 v192, v0, v154
	v_add_f32_e32 v193, v1, v155
	s_waitcnt lgkmcnt(1)
	v_mul_f32_e32 v194, v119, v193
	v_mul_f32_e32 v195, v119, v192
	v_fma_f32 v0, v118, v192, -v194
	v_fma_f32 v1, v118, v193, v195
	v_add_f32_e32 v192, v0, v156
	v_add_f32_e32 v193, v1, v157
	s_waitcnt lgkmcnt(0)
	v_mul_f32_e32 v194, v119, v193
	v_mul_f32_e32 v195, v119, v192
	v_fma_f32 v0, v118, v192, -v194
	v_fma_f32 v1, v118, v193, v195
	v_add_f32_e32 v192, v0, v158
	v_add_f32_e32 v193, v1, v159
.Ls5l_sdone1:
	global_store_dwordx2 v10, v[192:193], s[56:57]
	s_waitcnt vmcnt(0)
	v_cvt_pk_bf16_f32 v120, v20, v21
	v_cvt_pk_bf16_f32 v121, v22, v23
	v_cvt_pk_bf16_f32 v122, v24, v25
	v_cvt_pk_bf16_f32 v123, v26, v27
	v_cvt_pk_bf16_f32 v124, v28, v29
	v_cvt_pk_bf16_f32 v125, v30, v31
	v_cvt_pk_bf16_f32 v126, v32, v33
	v_cvt_pk_bf16_f32 v127, v34, v35
	s_nop 1
	v_mfma_f32_16x16x32_bf16 v[128:131], v[120:123], v[36:39], 0
	v_mfma_f32_16x16x32_bf16 v[132:135], v[124:127], v[36:39], 0
	v_mfma_f32_16x16x32_bf16 v[136:139], v[120:123], v[40:43], 0
	v_mfma_f32_16x16x32_bf16 v[140:143], v[124:127], v[40:43], 0
	v_mfma_f32_16x16x32_bf16 v[144:147], v[120:123], v[44:47], 0
	v_mfma_f32_16x16x32_bf16 v[148:151], v[124:127], v[44:47], 0
	v_mfma_f32_16x16x32_bf16 v[152:155], v[120:123], v[48:51], 0
	v_mfma_f32_16x16x32_bf16 v[156:159], v[124:127], v[48:51], 0
	v_mfma_f32_16x16x32_bf16 v[160:163], v[120:123], v[52:55], 0
	v_mfma_f32_16x16x32_bf16 v[164:167], v[124:127], v[52:55], 0
	v_mfma_f32_16x16x32_bf16 v[168:171], v[120:123], v[56:59], 0
	v_mfma_f32_16x16x32_bf16 v[172:175], v[124:127], v[56:59], 0
	v_mfma_f32_16x16x32_bf16 v[176:179], v[120:123], v[60:63], 0
	v_mfma_f32_16x16x32_bf16 v[180:183], v[124:127], v[60:63], 0
	v_mfma_f32_16x16x32_bf16 v[184:187], v[120:123], v[64:67], 0
	v_mfma_f32_16x16x32_bf16 v[188:191], v[124:127], v[64:67], 0
	ds_write_b32 v6, v128 offset:0
	ds_write_b32 v6, v129 offset:528
	ds_write_b32 v6, v130 offset:1056
	ds_write_b32 v6, v131 offset:1584
	ds_write_b32 v6, v132 offset:8448
	ds_write_b32 v6, v133 offset:8976
	ds_write_b32 v6, v134 offset:9504
	ds_write_b32 v6, v135 offset:10032
	ds_write_b32 v6, v136 offset:64
	ds_write_b32 v6, v137 offset:592
	ds_write_b32 v6, v138 offset:1120
	ds_write_b32 v6, v139 offset:1648
	ds_write_b32 v6, v140 offset:8512
	ds_write_b32 v6, v141 offset:9040
	ds_write_b32 v6, v142 offset:9568
	ds_write_b32 v6, v143 offset:10096
	ds_write_b32 v6, v144 offset:128
	ds_write_b32 v6, v145 offset:656
	ds_write_b32 v6, v146 offset:1184
	ds_write_b32 v6, v147 offset:1712
	ds_write_b32 v6, v148 offset:8576
	ds_write_b32 v6, v149 offset:9104
	ds_write_b32 v6, v150 offset:9632
	ds_write_b32 v6, v151 offset:10160
	ds_write_b32 v6, v152 offset:192
	ds_write_b32 v6, v153 offset:720
	ds_write_b32 v6, v154 offset:1248
	ds_write_b32 v6, v155 offset:1776
	ds_write_b32 v6, v156 offset:8640
	ds_write_b32 v6, v157 offset:9168
	ds_write_b32 v6, v158 offset:9696
	ds_write_b32 v6, v159 offset:10224
	ds_write_b32 v6, v160 offset:256
	ds_write_b32 v6, v161 offset:784
	ds_write_b32 v6, v162 offset:1312
	ds_write_b32 v6, v163 offset:1840
	ds_write_b32 v6, v164 offset:8704
	ds_write_b32 v6, v165 offset:9232
	ds_write_b32 v6, v166 offset:9760
	ds_write_b32 v6, v167 offset:10288
	ds_write_b32 v6, v168 offset:320
	ds_write_b32 v6, v169 offset:848
	ds_write_b32 v6, v170 offset:1376
	ds_write_b32 v6, v171 offset:1904
	ds_write_b32 v6, v172 offset:8768
	ds_write_b32 v6, v173 offset:9296
	ds_write_b32 v6, v174 offset:9824
	ds_write_b32 v6, v175 offset:10352
	ds_write_b32 v6, v176 offset:384
	ds_write_b32 v6, v177 offset:912
	ds_write_b32 v6, v178 offset:1440
	ds_write_b32 v6, v179 offset:1968
	ds_write_b32 v6, v180 offset:8832
	ds_write_b32 v6, v181 offset:9360
	ds_write_b32 v6, v182 offset:9888
	ds_write_b32 v6, v183 offset:10416
	ds_write_b32 v6, v184 offset:448
	ds_write_b32 v6, v185 offset:976
	ds_write_b32 v6, v186 offset:1504
	ds_write_b32 v6, v187 offset:2032
	s_nop 4
	ds_write_b32 v6, v188 offset:8896
	ds_write_b32 v6, v189 offset:9424
	ds_write_b32 v6, v190 offset:9952
	ds_write_b32 v6, v191 offset:10480
	v_mov_b32_e32 v192, 0
	v_mov_b32_e32 v193, 0
	s_waitcnt lgkmcnt(0)
	s_cmp_eq_u32 s54, 0
	s_cbranch_scc0 .Ls5l_bwd2
	ds_read_b64 v[128:129], v7 offset:0
	ds_read_b64 v[130:131], v7 offset:528
	ds_read_b64 v[132:133], v7 offset:1056
	ds_read_b64 v[134:135], v7 offset:1584
	ds_read_b64 v[136:137], v7 offset:2112
	ds_read_b64 v[138:139], v7 offset:2640
	ds_read_b64 v[140:141], v7 offset:3168
	ds_read_b64 v[142:143], v7 offset:3696
	ds_read_b64 v[144:145], v7 offset:4224
	ds_read_b64 v[146:147], v7 offset:4752
	ds_read_b64 v[148:149], v7 offset:5280
	ds_read_b64 v[150:151], v7 offset:5808
	ds_read_b64 v[152:153], v7 offset:6336
	ds_read_b64 v[154:155], v7 offset:6864
	ds_read_b64 v[156:157], v7 offset:7392
	ds_read_b64 v[158:159], v7 offset:7920
	s_waitcnt lgkmcnt(15)
	v_mul_f32_e32 v194, v69, v193
	v_mul_f32_e32 v195, v69, v192
	v_fma_f32 v0, v68, v192, -v194
	v_fma_f32 v1, v68, v193, v195
	v_add_f32_e32 v192, v0, v128
	v_add_f32_e32 v193, v1, v129
	s_waitcnt lgkmcnt(14)
	v_mul_f32_e32 v194, v69, v193
	v_mul_f32_e32 v195, v69, v192
	v_fma_f32 v0, v68, v192, -v194
	v_fma_f32 v1, v68, v193, v195
	v_add_f32_e32 v192, v0, v130
	v_add_f32_e32 v193, v1, v131
	s_waitcnt lgkmcnt(13)
	v_mul_f32_e32 v194, v69, v193
	v_mul_f32_e32 v195, v69, v192
	v_fma_f32 v0, v68, v192, -v194
	v_fma_f32 v1, v68, v193, v195
	v_add_f32_e32 v192, v0, v132
	v_add_f32_e32 v193, v1, v133
	s_waitcnt lgkmcnt(12)
	v_mul_f32_e32 v194, v69, v193
	v_mul_f32_e32 v195, v69, v192
	v_fma_f32 v0, v68, v192, -v194
	v_fma_f32 v1, v68, v193, v195
	v_add_f32_e32 v192, v0, v134
	v_add_f32_e32 v193, v1, v135
	s_waitcnt lgkmcnt(11)
	v_mul_f32_e32 v194, v69, v193
	v_mul_f32_e32 v195, v69, v192
	v_fma_f32 v0, v68, v192, -v194
	v_fma_f32 v1, v68, v193, v195
	v_add_f32_e32 v192, v0, v136
	v_add_f32_e32 v193, v1, v137
	s_waitcnt lgkmcnt(10)
	v_mul_f32_e32 v194, v69, v193
	v_mul_f32_e32 v195, v69, v192
	v_fma_f32 v0, v68, v192, -v194
	v_fma_f32 v1, v68, v193, v195
	v_add_f32_e32 v192, v0, v138
	v_add_f32_e32 v193, v1, v139
	s_waitcnt lgkmcnt(9)
	v_mul_f32_e32 v194, v69, v193
	v_mul_f32_e32 v195, v69, v192
	v_fma_f32 v0, v68, v192, -v194
	v_fma_f32 v1, v68, v193, v195
	v_add_f32_e32 v192, v0, v140
	v_add_f32_e32 v193, v1, v141
	s_waitcnt lgkmcnt(8)
	v_mul_f32_e32 v194, v69, v193
	v_mul_f32_e32 v195, v69, v192
	v_fma_f32 v0, v68, v192, -v194
	v_fma_f32 v1, v68, v193, v195
	v_add_f32_e32 v192, v0, v142
	v_add_f32_e32 v193, v1, v143
	ds_read_b64 v[128:129], v7 offset:8448
	ds_read_b64 v[130:131], v7 offset:8976
	ds_read_b64 v[132:133], v7 offset:9504
	ds_read_b64 v[134:135], v7 offset:10032
	ds_read_b64 v[136:137], v7 offset:10560
	ds_read_b64 v[138:139], v7 offset:11088
	ds_read_b64 v[140:141], v7 offset:11616
	ds_read_b64 v[142:143], v7 offset:12144
	s_waitcnt lgkmcnt(15)
	v_mul_f32_e32 v194, v69, v193
	v_mul_f32_e32 v195, v69, v192
	v_fma_f32 v0, v68, v192, -v194
	v_fma_f32 v1, v68, v193, v195
	v_add_f32_e32 v192, v0, v144
	v_add_f32_e32 v193, v1, v145
	s_waitcnt lgkmcnt(14)
	v_mul_f32_e32 v194, v69, v193
	v_mul_f32_e32 v195, v69, v192
	v_fma_f32 v0, v68, v192, -v194
	v_fma_f32 v1, v68, v193, v195
	v_add_f32_e32 v192, v0, v146
	v_add_f32_e32 v193, v1, v147
	s_waitcnt lgkmcnt(13)
	v_mul_f32_e32 v194, v69, v193
	v_mul_f32_e32 v195, v69, v192
	v_fma_f32 v0, v68, v192, -v194
	v_fma_f32 v1, v68, v193, v195
	v_add_f32_e32 v192, v0, v148
	v_add_f32_e32 v193, v1, v149
	s_waitcnt lgkmcnt(12)
	v_mul_f32_e32 v194, v69, v193
	v_mul_f32_e32 v195, v69, v192
	v_fma_f32 v0, v68, v192, -v194
	v_fma_f32 v1, v68, v193, v195
	v_add_f32_e32 v192, v0, v150
	v_add_f32_e32 v193, v1, v151
	s_waitcnt lgkmcnt(11)
	v_mul_f32_e32 v194, v69, v193
	v_mul_f32_e32 v195, v69, v192
	v_fma_f32 v0, v68, v192, -v194
	v_fma_f32 v1, v68, v193, v195
	v_add_f32_e32 v192, v0, v152
	v_add_f32_e32 v193, v1, v153
	s_waitcnt lgkmcnt(10)
	v_mul_f32_e32 v194, v69, v193
	v_mul_f32_e32 v195, v69, v192
	v_fma_f32 v0, v68, v192, -v194
	v_fma_f32 v1, v68, v193, v195
	v_add_f32_e32 v192, v0, v154
	v_add_f32_e32 v193, v1, v155
	s_waitcnt lgkmcnt(9)
	v_mul_f32_e32 v194, v69, v193
	v_mul_f32_e32 v195, v69, v192
	v_fma_f32 v0, v68, v192, -v194
	v_fma_f32 v1, v68, v193, v195
	v_add_f32_e32 v192, v0, v156
	v_add_f32_e32 v193, v1, v157
	s_waitcnt lgkmcnt(8)
	v_mul_f32_e32 v194, v69, v193
	v_mul_f32_e32 v195, v69, v192
	v_fma_f32 v0, v68, v192, -v194
	v_fma_f32 v1, v68, v193, v195
	v_add_f32_e32 v192, v0, v158
	v_add_f32_e32 v193, v1, v159
	ds_read_b64 v[144:145], v7 offset:12672
	ds_read_b64 v[146:147], v7 offset:13200
	ds_read_b64 v[148:149], v7 offset:13728
	ds_read_b64 v[150:151], v7 offset:14256
	ds_read_b64 v[152:153], v7 offset:14784
	ds_read_b64 v[154:155], v7 offset:15312
	ds_read_b64 v[156:157], v7 offset:15840
	ds_read_b64 v[158:159], v7 offset:16368
	s_waitcnt lgkmcnt(15)
	v_mul_f32_e32 v194, v69, v193
	v_mul_f32_e32 v195, v69, v192
	v_fma_f32 v0, v68, v192, -v194
	v_fma_f32 v1, v68, v193, v195
	v_add_f32_e32 v192, v0, v128
	v_add_f32_e32 v193, v1, v129
	s_waitcnt lgkmcnt(14)
	v_mul_f32_e32 v194, v69, v193
	v_mul_f32_e32 v195, v69, v192
	v_fma_f32 v0, v68, v192, -v194
	v_fma_f32 v1, v68, v193, v195
	v_add_f32_e32 v192, v0, v130
	v_add_f32_e32 v193, v1, v131
	s_waitcnt lgkmcnt(13)
	v_mul_f32_e32 v194, v69, v193
	v_mul_f32_e32 v195, v69, v192
	v_fma_f32 v0, v68, v192, -v194
	v_fma_f32 v1, v68, v193, v195
	v_add_f32_e32 v192, v0, v132
	v_add_f32_e32 v193, v1, v133
	s_waitcnt lgkmcnt(12)
	v_mul_f32_e32 v194, v69, v193
	v_mul_f32_e32 v195, v69, v192
	v_fma_f32 v0, v68, v192, -v194
	v_fma_f32 v1, v68, v193, v195
	v_add_f32_e32 v192, v0, v134
	v_add_f32_e32 v193, v1, v135
	s_waitcnt lgkmcnt(11)
	v_mul_f32_e32 v194, v69, v193
	v_mul_f32_e32 v195, v69, v192
	v_fma_f32 v0, v68, v192, -v194
	v_fma_f32 v1, v68, v193, v195
	v_add_f32_e32 v192, v0, v136
	v_add_f32_e32 v193, v1, v137
	s_waitcnt lgkmcnt(10)
	v_mul_f32_e32 v194, v69, v193
	v_mul_f32_e32 v195, v69, v192
	v_fma_f32 v0, v68, v192, -v194
	v_fma_f32 v1, v68, v193, v195
	v_add_f32_e32 v192, v0, v138
	v_add_f32_e32 v193, v1, v139
	s_waitcnt lgkmcnt(9)
	v_mul_f32_e32 v194, v69, v193
	v_mul_f32_e32 v195, v69, v192
	v_fma_f32 v0, v68, v192, -v194
	v_fma_f32 v1, v68, v193, v195
	v_add_f32_e32 v192, v0, v140
	v_add_f32_e32 v193, v1, v141
	s_waitcnt lgkmcnt(8)
	v_mul_f32_e32 v194, v69, v193
	v_mul_f32_e32 v195, v69, v192
	v_fma_f32 v0, v68, v192, -v194
	v_fma_f32 v1, v68, v193, v195
	v_add_f32_e32 v192, v0, v142
	v_add_f32_e32 v193, v1, v143
	s_waitcnt lgkmcnt(7)
	v_mul_f32_e32 v194, v69, v193
	v_mul_f32_e32 v195, v69, v192
	v_fma_f32 v0, v68, v192, -v194
	v_fma_f32 v1, v68, v193, v195
	v_add_f32_e32 v192, v0, v144
	v_add_f32_e32 v193, v1, v145
	s_waitcnt lgkmcnt(6)
	v_mul_f32_e32 v194, v69, v193
	v_mul_f32_e32 v195, v69, v192
	v_fma_f32 v0, v68, v192, -v194
	v_fma_f32 v1, v68, v193, v195
	v_add_f32_e32 v192, v0, v146
	v_add_f32_e32 v193, v1, v147
	s_waitcnt lgkmcnt(5)
	v_mul_f32_e32 v194, v69, v193
	v_mul_f32_e32 v195, v69, v192
	v_fma_f32 v0, v68, v192, -v194
	v_fma_f32 v1, v68, v193, v195
	v_add_f32_e32 v192, v0, v148
	v_add_f32_e32 v193, v1, v149
	s_waitcnt lgkmcnt(4)
	v_mul_f32_e32 v194, v69, v193
	v_mul_f32_e32 v195, v69, v192
	v_fma_f32 v0, v68, v192, -v194
	v_fma_f32 v1, v68, v193, v195
	v_add_f32_e32 v192, v0, v150
	v_add_f32_e32 v193, v1, v151
	s_waitcnt lgkmcnt(3)
	v_mul_f32_e32 v194, v69, v193
	v_mul_f32_e32 v195, v69, v192
	v_fma_f32 v0, v68, v192, -v194
	v_fma_f32 v1, v68, v193, v195
	v_add_f32_e32 v192, v0, v152
	v_add_f32_e32 v193, v1, v153
	s_waitcnt lgkmcnt(2)
	v_mul_f32_e32 v194, v69, v193
	v_mul_f32_e32 v195, v69, v192
	v_fma_f32 v0, v68, v192, -v194
	v_fma_f32 v1, v68, v193, v195
	v_add_f32_e32 v192, v0, v154
	v_add_f32_e32 v193, v1, v155
	s_waitcnt lgkmcnt(1)
	v_mul_f32_e32 v194, v69, v193
	v_mul_f32_e32 v195, v69, v192
	v_fma_f32 v0, v68, v192, -v194
	v_fma_f32 v1, v68, v193, v195
	v_add_f32_e32 v192, v0, v156
	v_add_f32_e32 v193, v1, v157
	s_waitcnt lgkmcnt(0)
	v_mul_f32_e32 v194, v69, v193
	v_mul_f32_e32 v195, v69, v192
	v_fma_f32 v0, v68, v192, -v194
	v_fma_f32 v1, v68, v193, v195
	v_add_f32_e32 v192, v0, v158
	v_add_f32_e32 v193, v1, v159
	s_branch .Ls5l_sdone2

.Ls5l_sdone2:
	global_store_dwordx2 v10, v[192:193], s[50:51]
	s_waitcnt vmcnt(0) lgkmcnt(0)
	s_branch .Ls5l_back

.LBB0_642:
	s_or_b64 exec, exec, s[38:39]
	s_waitcnt lgkmcnt(0)
	s_barrier
	ds_read_b32 v0, v208
	s_movk_i32 s4, 0x35f
	s_waitcnt lgkmcnt(0)
	v_cmp_lt_i32_e32 vcc, s4, v0
	v_readfirstlane_b32 s60, v0
	s_nop 0
	s_add_u32 s99, s60, 0x630
	s_sub_u32 s98, s60, 48
	s_add_u32 s100, s60, 720
	s_cmp_lt_u32 s60, 96
	s_cselect_b32 s98, s98, s100
	s_cmp_lt_u32 s60, 48
	s_cselect_b32 s60, s99, s98
	s_cbranch_vccnz .LBB0_704
	v_readlane_b32 s44, v237, 9
	s_mul_i32 s40, s36, 0x5000
	s_lshl_b64 s[38:39], s[36:37], 12
	v_readlane_b32 s52, v237, 17
	s_mul_hi_i32 s35, s36, 0x5000
	v_readlane_b32 s53, v237, 18
	s_add_u32 s40, s52, s40
	v_readlane_b32 s54, v237, 19
	s_addc_u32 s41, s53, s35
	v_readlane_b32 s4, v235, 61
	v_readlane_b32 s55, v237, 20
	s_add_u32 s42, s54, s38
	v_readlane_b32 s5, v235, 62
	v_writelane_b32 v234, s16, 0
	s_addc_u32 s43, s55, s39
	s_lshl_b64 s[38:39], s[4:5], 2
	v_writelane_b32 v234, s17, 1
	s_mov_b32 s52, s18
	v_readlane_b32 s4, v237, 25
	v_readlane_b32 s8, v237, 29
	v_readlane_b32 s16, v237, 37
	v_readlane_b32 s17, v237, 38
	v_readlane_b32 s45, v237, 10
	v_readlane_b32 s6, v237, 27
	v_readlane_b32 s9, v237, 30
	v_readlane_b32 s16, v234, 0
	s_add_u32 s44, s8, s38
	s_mov_b32 s6, s52
	v_readlane_b32 s17, v234, 1
	s_addc_u32 s45, s9, s39
	v_readlane_b32 s46, v237, 11
	v_readlane_b32 s47, v237, 12
	v_readlane_b32 s48, v237, 13
	v_readlane_b32 s49, v237, 14
	v_readlane_b32 s50, v237, 15
	v_readlane_b32 s51, v237, 16
	v_readlane_b32 s56, v237, 21
	v_readlane_b32 s57, v237, 22
	v_readlane_b32 s58, v237, 23
	v_readlane_b32 s59, v237, 24
	v_readlane_b32 s5, v237, 26
	v_readlane_b32 s7, v237, 28
	v_readlane_b32 s10, v237, 31
	v_readlane_b32 s11, v237, 32
	v_readlane_b32 s12, v237, 33
	v_readlane_b32 s13, v237, 34
	v_readlane_b32 s14, v237, 35
	v_readlane_b32 s15, v237, 36
	v_readlane_b32 s18, v237, 39
	v_readlane_b32 s19, v237, 40
	s_branch .LBB0_646

.LBB0_645:
	s_or_b64 exec, exec, s[38:39]
	s_waitcnt lgkmcnt(0)
	s_barrier
	ds_read_b32 v0, v208
	s_movk_i32 s4, 0x35f
	s_waitcnt lgkmcnt(0)
	v_cmp_lt_i32_e32 vcc, s4, v0
	v_readfirstlane_b32 s60, v0
	s_nop 0
	s_add_u32 s99, s60, 0x630
	s_sub_u32 s98, s60, 48
	s_add_u32 s100, s60, 720
	s_cmp_lt_u32 s60, 96
	s_cselect_b32 s98, s98, s100
	s_cmp_lt_u32 s60, 48
	s_cselect_b32 s60, s99, s98
	s_cbranch_vccnz .LBB0_704
